# weight-prep tile items (M1/M2 queues): all eight row-group loads requested before the first wait
# speedup vs baseline: 1.0772x; 1.0028x over previous
.LBB0_557:
	s_or_b64 exec, exec, s[10:11]
	v_mov_b32_e32 v0, s71
	s_waitcnt lgkmcnt(0)
	s_barrier
	ds_read_b32 v0, v0
	s_movk_i32 s4, 0xa7f
	s_mov_b64 s[10:11], -1
	s_waitcnt lgkmcnt(0)
	v_cmp_lt_i32_e32 vcc, s4, v0
	v_readfirstlane_b32 s91, v0
	s_cbranch_vccnz .LBB0_552
	s_cmpk_gt_i32 s91, 0xbf
	s_cbranch_scc0 .LBB0_790
	s_cmpk_gt_u32 s91, 0x1bf
	s_cbranch_scc0 .LBB0_656
	s_cmpk_gt_u32 s91, 0x7bf
	s_cbranch_scc0 .LBB0_643
	v_mov_b32_e32 v8, v203
	s_lshl_b32 s5, s91, 3
	v_readfirstlane_b32 s4, v8
	s_ashr_i32 s4, s4, 6
	s_add_i32 s31, s5, s4
	s_addk_i32 s31, 0xc200
	s_cmpk_gt_i32 s31, 0x15ff
	s_cbranch_scc1 .LBB0_642
	s_mulk_i32 s4, 0x2100
	s_add_i32 s30, s4, 0
	v_and_b32_e32 v10, 63, v8
	s_cmpk_gt_i32 s31, 0x17f
	s_cbranch_scc0 .LBB0_616
	s_cmpk_gt_u32 s31, 0x2ff
	s_cbranch_scc0 .LBB0_613
	s_cmpk_gt_u32 s31, 0x37f
	s_cbranch_scc0 .LBB0_610
	s_cmpk_gt_u32 s31, 0x57f
	s_cbranch_scc0 .LBB0_607
	s_cmpk_gt_u32 s31, 0xaff
	s_cbranch_scc0 .LBB0_588
	s_cmpk_gt_u32 s31, 0x107f
	s_cbranch_scc0 .LBB0_569
	s_movk_i32 s4, 0xd8
	v_readlane_b32 s10, v250, 57
	v_readlane_b32 s11, v250, 58
	s_load_dwordx2 s[4:5], s[10:11], s4 offset:0x0
	s_mul_i32 s10, s52, 0xb00000
	v_and_b32_e32 v3, 7, v8
	v_lshlrev_b32_e32 v2, 4, v3
	v_lshrrev_b32_e32 v9, 3, v10
	s_waitcnt lgkmcnt(0)
	s_add_u32 s10, s4, s10
	s_addc_u32 s11, s5, 0
	s_lshl_b32 s4, s31, 1
	s_add_i32 s4, s4, 0x1df00
	s_and_b32 s5, s4, 0x1ffc0
	s_lshl_b32 s4, s31, 5
	s_and_b32 s4, s4, 0x3e0
	v_lshl_or_b32 v0, s4, 2, v2
	v_lshl_add_u64 v[12:13], s[10:11], 0, v[0:1]
	v_or_b32_e32 v0, s5, v9
	v_lshlrev_b32_e32 v0, 12, v0
	v_lshl_add_u64 v[4:5], v[12:13], 0, v[0:1]
	v_mov_b32_e32 v68, 0x8000
	v_mov_b32_e32 v69, 0
	v_lshl_add_u64 v[70:71], v[4:5], 0, v[68:69]
	global_load_dwordx4 v[40:43], v[70:71], off
	v_lshl_add_u64 v[70:71], v[70:71], 0, v[68:69]
	global_load_dwordx4 v[44:47], v[70:71], off
	v_lshl_add_u64 v[70:71], v[70:71], 0, v[68:69]
	global_load_dwordx4 v[48:51], v[70:71], off
	v_lshl_add_u64 v[70:71], v[70:71], 0, v[68:69]
	global_load_dwordx4 v[52:55], v[70:71], off
	v_lshl_add_u64 v[70:71], v[70:71], 0, v[68:69]
	global_load_dwordx4 v[56:59], v[70:71], off
	v_lshl_add_u64 v[70:71], v[70:71], 0, v[68:69]
	global_load_dwordx4 v[60:63], v[70:71], off
	v_lshl_add_u64 v[70:71], v[70:71], 0, v[68:69]
	global_load_dwordx4 v[64:67], v[70:71], off
	global_load_dwordx4 v[4:7], v[4:5], off
	v_mul_u32_u24_e32 v11, 0x84, v9
	v_add3_u32 v11, s30, v2, v11
	v_or_b32_e32 v30, 8, v9
	v_add_u32_e32 v14, 0x420, v11
	v_or_b32_e32 v31, 16, v9
	v_or_b32_e32 v32, 24, v9
	v_readlane_b32 s10, v249, 6
	s_waitcnt vmcnt(0)
	ds_write2_b32 v11, v4, v5 offset1:1
	ds_write2_b32 v11, v6, v7 offset0:2 offset1:3
	v_or_b32_e32 v4, s5, v30
	v_lshlrev_b32_e32 v4, 12, v4
	v_mov_b32_e32 v5, v1
	v_lshl_add_u64 v[4:5], v[12:13], 0, v[4:5]
	v_mov_b64_e32 v[4:5], v[40:41]
	v_mov_b64_e32 v[6:7], v[42:43]
	s_waitcnt vmcnt(0)
	ds_write2_b32 v14, v4, v5 offset1:1
	v_add_u32_e32 v4, 0x428, v11
	ds_write2_b32 v4, v6, v7 offset1:1
	v_or_b32_e32 v4, s5, v31
	v_lshlrev_b32_e32 v4, 12, v4
	v_mov_b32_e32 v5, v1
	v_lshl_add_u64 v[4:5], v[12:13], 0, v[4:5]
	v_mov_b64_e32 v[4:5], v[44:45]
	v_mov_b64_e32 v[6:7], v[46:47]
	v_add_u32_e32 v14, 0x840, v11
	s_waitcnt vmcnt(0)
	ds_write2_b32 v14, v4, v5 offset1:1
	v_add_u32_e32 v4, 0x848, v11
	ds_write2_b32 v4, v6, v7 offset1:1
	v_or_b32_e32 v4, s5, v32
	v_lshlrev_b32_e32 v4, 12, v4
	v_mov_b32_e32 v5, v1
	v_lshl_add_u64 v[4:5], v[12:13], 0, v[4:5]
	v_mov_b64_e32 v[4:5], v[48:49]
	v_mov_b64_e32 v[6:7], v[50:51]
	v_add_u32_e32 v14, 0xc60, v11
	s_lshl_b32 s5, s5, 1
	s_add_u32 s10, s10, s5
	v_readlane_b32 s5, v249, 8
	s_addc_u32 s11, s5, 0
	s_waitcnt vmcnt(0)
	ds_write2_b32 v14, v4, v5 offset1:1
	v_add_u32_e32 v4, 0xc68, v11
	ds_write2_b32 v4, v6, v7 offset1:1
	v_or_b32_e32 v4, 0x20000, v0
	v_mov_b32_e32 v5, v1
	v_lshl_add_u64 v[4:5], v[12:13], 0, v[4:5]
	v_mov_b64_e32 v[4:5], v[52:53]
	v_mov_b64_e32 v[6:7], v[54:55]
	v_add_u32_e32 v14, 0x1080, v11
	s_waitcnt vmcnt(0)
	ds_write2_b32 v14, v4, v5 offset1:1
	v_add_u32_e32 v4, 0x1088, v11
	ds_write2_b32 v4, v6, v7 offset1:1
	v_or_b32_e32 v4, 0x28000, v0
	v_mov_b32_e32 v5, v1
	v_lshl_add_u64 v[4:5], v[12:13], 0, v[4:5]
	v_mov_b64_e32 v[4:5], v[56:57]
	v_mov_b64_e32 v[6:7], v[58:59]
	v_add_u32_e32 v14, 0x14a0, v11
	s_waitcnt vmcnt(0)
	ds_write2_b32 v14, v4, v5 offset1:1
	v_add_u32_e32 v4, 0x14a8, v11
	ds_write2_b32 v4, v6, v7 offset1:1
	v_or_b32_e32 v4, 0x30000, v0
	v_mov_b32_e32 v5, v1
	v_lshl_add_u64 v[4:5], v[12:13], 0, v[4:5]
	v_mov_b64_e32 v[4:5], v[60:61]
	v_mov_b64_e32 v[6:7], v[62:63]
	v_add_u32_e32 v14, 0x18c0, v11
	v_or_b32_e32 v0, 0x38000, v0
	s_waitcnt vmcnt(0)
	ds_write2_b32 v14, v4, v5 offset1:1
	v_add_u32_e32 v4, 0x18c8, v11
	ds_write2_b32 v4, v6, v7 offset1:1
	v_lshl_add_u64 v[4:5], v[12:13], 0, v[0:1]
	v_mov_b64_e32 v[4:5], v[64:65]
	v_mov_b64_e32 v[6:7], v[66:67]
	v_add_u32_e32 v0, 0x1ce0, v11
	s_waitcnt vmcnt(0)
	ds_write2_b32 v0, v4, v5 offset1:1
	v_add_u32_e32 v0, 0x1ce8, v11
	ds_write2_b32 v0, v6, v7 offset1:1
	v_mul_u32_u24_e32 v0, 0x420, v3
	v_lshlrev_b32_e32 v4, 2, v9
	s_waitcnt lgkmcnt(0)
	v_or_b32_e32 v11, s4, v9
	v_add3_u32 v9, s30, v0, v4
	ds_read2_b32 v[12:13], v9 offset0:198 offset1:206
	ds_read2_b32 v[14:15], v9 offset0:231 offset1:239
	ds_read2_b32 v[16:17], v9 offset0:132 offset1:140
	ds_read2_b32 v[18:19], v9 offset0:165 offset1:173
	ds_read2_b32 v[20:21], v9 offset0:66 offset1:74
	ds_read2_b32 v[22:23], v9 offset0:99 offset1:107
	ds_read2_b32 v[24:25], v9 offset0:33 offset1:41
	ds_read2_b32 v[26:27], v9 offset1:8
	v_mov_b32_e32 v3, v1
	v_mul_u32_u24_e32 v0, 0xb00, v11
	v_lshl_add_u64 v[2:3], s[10:11], 0, v[2:3]
	v_lshlrev_b32_e32 v0, 1, v0
	v_lshl_add_u64 v[28:29], v[2:3], 0, v[0:1]
	v_or_b32_e32 v0, s4, v30
	v_mul_u32_u24_e32 v0, 0xb00, v0
	s_waitcnt lgkmcnt(6)
	v_cvt_pk_bf16_f32 v7, v12, v14
	s_waitcnt lgkmcnt(4)
	v_cvt_pk_bf16_f32 v6, v16, v18
	s_waitcnt lgkmcnt(2)
	v_cvt_pk_bf16_f32 v5, v20, v22
	s_waitcnt lgkmcnt(0)
	v_cvt_pk_bf16_f32 v4, v26, v24
	v_lshlrev_b32_e32 v0, 1, v0
	global_store_dwordx4 v[28:29], v[4:7], off
	s_mov_b64 s[10:11], 0
	s_nop 0
	v_cvt_pk_bf16_f32 v7, v13, v15
	v_cvt_pk_bf16_f32 v6, v17, v19
	v_cvt_pk_bf16_f32 v5, v21, v23
	v_cvt_pk_bf16_f32 v4, v27, v25
	v_lshl_add_u64 v[12:13], v[2:3], 0, v[0:1]
	global_store_dwordx4 v[12:13], v[4:7], off
	v_or_b32_e32 v0, s4, v31
	ds_read2_b32 v[12:13], v9 offset0:214 offset1:222
	ds_read2_b32 v[14:15], v9 offset0:247 offset1:255
	ds_read2_b32 v[16:17], v9 offset0:148 offset1:156
	ds_read2_b32 v[18:19], v9 offset0:181 offset1:189
	ds_read2_b32 v[20:21], v9 offset0:82 offset1:90
	ds_read2_b32 v[22:23], v9 offset0:115 offset1:123
	ds_read2_b32 v[24:25], v9 offset0:16 offset1:24
	ds_read2_b32 v[26:27], v9 offset0:49 offset1:57
	v_mul_u32_u24_e32 v0, 0xb00, v0
	v_lshlrev_b32_e32 v0, 1, v0
	v_lshl_add_u64 v[28:29], v[2:3], 0, v[0:1]
	v_or_b32_e32 v0, s4, v32
	v_mul_u32_u24_e32 v0, 0xb00, v0
	s_waitcnt lgkmcnt(6)
	v_cvt_pk_bf16_f32 v7, v12, v14
	s_waitcnt lgkmcnt(4)
	v_cvt_pk_bf16_f32 v6, v16, v18
	s_waitcnt lgkmcnt(2)
	v_cvt_pk_bf16_f32 v5, v20, v22
	s_waitcnt lgkmcnt(0)
	v_cvt_pk_bf16_f32 v4, v24, v26
	v_lshlrev_b32_e32 v0, 1, v0
	global_store_dwordx4 v[28:29], v[4:7], off
	v_lshl_add_u64 v[2:3], v[2:3], 0, v[0:1]
	s_nop 0
	v_cvt_pk_bf16_f32 v7, v13, v15
	v_cvt_pk_bf16_f32 v6, v17, v19
	v_cvt_pk_bf16_f32 v5, v21, v23
	v_cvt_pk_bf16_f32 v4, v25, v27
	global_store_dwordx4 v[2:3], v[4:7], off
	s_waitcnt lgkmcnt(0)
.LBB0_569:
	s_andn2_b64 vcc, exec, s[10:11]
	s_cbranch_vccnz .LBB0_587
	s_movk_i32 s4, 0xd0
	v_readlane_b32 s12, v250, 57
	v_readlane_b32 s13, v250, 58
	s_load_dwordx2 s[4:5], s[12:13], s4 offset:0x0
	s_movk_i32 s10, 0xc0
	s_load_dwordx2 s[10:11], s[12:13], s10 offset:0x0
	s_mul_i32 s12, s52, 0xb00000
	s_waitcnt lgkmcnt(0)
	s_add_u32 s12, s4, s12
	s_addc_u32 s13, s5, 0
	v_readlane_b32 s4, v249, 9
	v_readlane_b32 s5, v249, 10
	s_lshl_b64 s[4:5], s[4:5], 2
	s_add_u32 s26, s10, s4
	s_addc_u32 s27, s11, s5
	s_add_i32 s4, s31, 0xf500
	s_and_b32 s5, s4, 0xffff
	s_mul_i32 s5, s5, 0xba2f
	s_lshr_b32 s18, s5, 16
	s_lshr_b32 s5, s5, 22
	s_mulk_i32 s5, 0x58
	s_sub_i32 s4, s4, s5
	s_lshl_b32 s4, s4, 5
	v_and_b32_e32 v12, 7, v8
	s_and_b32 s4, s4, 0xffe0
	v_lshlrev_b32_e32 v11, 2, v12
	s_and_b32 s5, s18, 0xffc0
	v_or_b32_e32 v0, s4, v11
	v_lshrrev_b32_e32 v9, 3, v10
	v_lshlrev_b32_e32 v0, 2, v0
	v_or_b32_e32 v13, s5, v9
	v_lshl_add_u64 v[6:7], s[12:13], 0, v[0:1]
	v_mul_u32_u24_e32 v0, 0xb00, v13
	v_lshlrev_b32_e32 v0, 2, v0
	v_lshl_add_u64 v[2:3], v[6:7], 0, v[0:1]
	v_mov_b32_e32 v68, 0x16000
	v_mov_b32_e32 v69, 0
	v_lshl_add_u64 v[70:71], v[2:3], 0, v[68:69]
	global_load_dwordx4 v[40:43], v[70:71], off
	v_lshl_add_u64 v[70:71], v[70:71], 0, v[68:69]
	global_load_dwordx4 v[44:47], v[70:71], off
	v_lshl_add_u64 v[70:71], v[70:71], 0, v[68:69]
	global_load_dwordx4 v[48:51], v[70:71], off
	v_lshl_add_u64 v[70:71], v[70:71], 0, v[68:69]
	global_load_dwordx4 v[52:55], v[70:71], off
	v_lshl_add_u64 v[70:71], v[70:71], 0, v[68:69]
	global_load_dwordx4 v[56:59], v[70:71], off
	v_lshl_add_u64 v[70:71], v[70:71], 0, v[68:69]
	global_load_dwordx4 v[60:63], v[70:71], off
	v_lshl_add_u64 v[70:71], v[70:71], 0, v[68:69]
	global_load_dwordx4 v[64:67], v[70:71], off
	global_load_dwordx4 v[2:5], v[2:3], off
	s_cmp_lg_u64 s[10:11], 0
	s_cselect_b64 s[28:29], -1, 0
	s_cmp_eq_u64 s[10:11], 0
	s_cbranch_scc1 .LBB0_572
	v_lshlrev_b32_e32 v0, 2, v13
	global_load_dword v72, v0, s[26:27] offset:128
	global_load_dword v0, v0, s[26:27]
	s_waitcnt vmcnt(0)
	v_pk_mul_f32 v[4:5], v[4:5], v[0:1] op_sel_hi:[1,0]
	v_pk_mul_f32 v[2:3], v[2:3], v[0:1] op_sel_hi:[1,0]
.LBB0_572:
	v_lshl_add_u32 v13, v11, 2, s30
	s_movk_i32 s10, 0x84
	v_mad_u32_u24 v0, v9, s10, v13
	v_or_b32_e32 v11, 8, v9
	s_waitcnt vmcnt(0)
	ds_write2_b32 v0, v2, v3 offset1:1
	ds_write2_b32 v0, v4, v5 offset0:2 offset1:3
	v_or_b32_e32 v0, s5, v11
	v_mul_u32_u24_e32 v0, 0xb00, v0
	v_lshlrev_b32_e32 v0, 2, v0
	v_lshl_add_u64 v[2:3], v[6:7], 0, v[0:1]
	v_mov_b64_e32 v[2:3], v[40:41]
	v_mov_b64_e32 v[4:5], v[42:43]
	v_cndmask_b32_e64 v0, 0, 1, s[28:29]
	v_cmp_ne_u32_e64 s[10:11], 1, v0
	s_andn2_b64 vcc, exec, s[28:29]
	v_add_lshl_u32 v15, v9, s5, 2
	s_cbranch_vccnz .LBB0_574
	global_load_dword v0, v15, s[26:27] offset:32
	s_waitcnt vmcnt(0)
	v_pk_mul_f32 v[4:5], v[4:5], v[0:1] op_sel_hi:[1,0]
	v_pk_mul_f32 v[2:3], v[2:3], v[0:1] op_sel_hi:[1,0]
.LBB0_574:
	v_mul_u32_u24_e32 v0, 0x84, v9
	v_add_u32_e32 v16, v0, v13
	v_add_u32_e32 v0, 0x420, v16
	s_waitcnt vmcnt(0)
	ds_write2_b32 v0, v2, v3 offset1:1
	v_add_u32_e32 v0, 0x428, v16
	v_or_b32_e32 v13, 16, v9
	ds_write2_b32 v0, v4, v5 offset1:1
	v_or_b32_e32 v0, s5, v13
	v_mul_u32_u24_e32 v0, 0xb00, v0
	v_lshlrev_b32_e32 v0, 2, v0
	v_lshl_add_u64 v[2:3], v[6:7], 0, v[0:1]
	v_mov_b64_e32 v[2:3], v[44:45]
	v_mov_b64_e32 v[4:5], v[46:47]
	s_and_b64 vcc, exec, s[10:11]
	s_cbranch_vccnz .LBB0_576
	global_load_dword v0, v15, s[26:27] offset:64
	s_waitcnt vmcnt(0)
	v_pk_mul_f32 v[4:5], v[4:5], v[0:1] op_sel_hi:[1,0]
	v_pk_mul_f32 v[2:3], v[2:3], v[0:1] op_sel_hi:[1,0]
.LBB0_576:
	v_add_u32_e32 v0, 0x840, v16
	s_waitcnt vmcnt(0)
	ds_write2_b32 v0, v2, v3 offset1:1
	v_add_u32_e32 v0, 0x848, v16
	v_or_b32_e32 v14, 24, v9
	ds_write2_b32 v0, v4, v5 offset1:1
	v_or_b32_e32 v0, s5, v14
	v_mul_u32_u24_e32 v0, 0xb00, v0
	v_lshlrev_b32_e32 v0, 2, v0
	v_lshl_add_u64 v[2:3], v[6:7], 0, v[0:1]
	v_mov_b64_e32 v[2:3], v[48:49]
	v_mov_b64_e32 v[4:5], v[50:51]
	s_and_b64 vcc, exec, s[10:11]
	s_cbranch_vccnz .LBB0_578
	global_load_dword v0, v15, s[26:27] offset:96
	s_waitcnt vmcnt(0)
	v_pk_mul_f32 v[4:5], v[4:5], v[0:1] op_sel_hi:[1,0]
	v_pk_mul_f32 v[2:3], v[2:3], v[0:1] op_sel_hi:[1,0]
.LBB0_578:
	v_add_u32_e32 v0, 0xc60, v16
	s_waitcnt vmcnt(0)
	ds_write2_b32 v0, v2, v3 offset1:1
	v_add_u32_e32 v0, 0xc68, v16
	ds_write2_b32 v0, v4, v5 offset1:1
	v_or3_b32 v0, v9, s5, 32
	v_mul_u32_u24_e32 v0, 0xb00, v0
	v_lshlrev_b32_e32 v0, 2, v0
	v_lshl_add_u64 v[2:3], v[6:7], 0, v[0:1]
	v_mov_b64_e32 v[2:3], v[52:53]
	v_mov_b64_e32 v[4:5], v[54:55]
	s_and_b64 vcc, exec, s[10:11]
	s_cbranch_vccnz .LBB0_580
	global_load_dword v0, v15, s[26:27] offset:128
	s_waitcnt vmcnt(0)
	v_pk_mul_f32 v[4:5], v[4:5], v[0:1] op_sel_hi:[1,0]
	v_pk_mul_f32 v[2:3], v[2:3], v[0:1] op_sel_hi:[1,0]
.LBB0_580:
	v_add_u32_e32 v0, 0x1080, v16
	s_waitcnt vmcnt(0)
	ds_write2_b32 v0, v2, v3 offset1:1
	v_add_u32_e32 v0, 0x1088, v16
	ds_write2_b32 v0, v4, v5 offset1:1
	v_or3_b32 v0, v9, s5, 40
	v_mul_u32_u24_e32 v0, 0xb00, v0
	v_lshlrev_b32_e32 v0, 2, v0
	v_lshl_add_u64 v[2:3], v[6:7], 0, v[0:1]
	v_mov_b64_e32 v[2:3], v[56:57]
	v_mov_b64_e32 v[4:5], v[58:59]
	s_and_b64 vcc, exec, s[10:11]
	s_cbranch_vccnz .LBB0_582
	global_load_dword v0, v15, s[26:27] offset:160
	s_waitcnt vmcnt(0)
	v_pk_mul_f32 v[4:5], v[4:5], v[0:1] op_sel_hi:[1,0]
	v_pk_mul_f32 v[2:3], v[2:3], v[0:1] op_sel_hi:[1,0]
.LBB0_582:
	v_add_u32_e32 v0, 0x14a0, v16
	s_waitcnt vmcnt(0)
	ds_write2_b32 v0, v2, v3 offset1:1
	v_add_u32_e32 v0, 0x14a8, v16
	ds_write2_b32 v0, v4, v5 offset1:1
	v_or3_b32 v0, v9, s5, 48
	v_mul_u32_u24_e32 v0, 0xb00, v0
	v_lshlrev_b32_e32 v0, 2, v0
	v_lshl_add_u64 v[2:3], v[6:7], 0, v[0:1]
	v_mov_b64_e32 v[2:3], v[60:61]
	v_mov_b64_e32 v[4:5], v[62:63]
	s_and_b64 vcc, exec, s[10:11]
	s_cbranch_vccnz .LBB0_584
	global_load_dword v0, v15, s[26:27] offset:192
	s_waitcnt vmcnt(0)
	v_pk_mul_f32 v[4:5], v[4:5], v[0:1] op_sel_hi:[1,0]
	v_pk_mul_f32 v[2:3], v[2:3], v[0:1] op_sel_hi:[1,0]
.LBB0_584:
	v_add_u32_e32 v0, 0x18c0, v16
	s_waitcnt vmcnt(0)
	ds_write2_b32 v0, v2, v3 offset1:1
	v_add_u32_e32 v0, 0x18c8, v16
	ds_write2_b32 v0, v4, v5 offset1:1
	v_or3_b32 v0, v9, s5, 56
	v_mul_u32_u24_e32 v0, 0xb00, v0
	v_lshlrev_b32_e32 v0, 2, v0
	v_lshl_add_u64 v[2:3], v[6:7], 0, v[0:1]
	v_mov_b64_e32 v[2:3], v[64:65]
	v_mov_b64_e32 v[4:5], v[66:67]
	s_and_b64 vcc, exec, s[10:11]
	s_cbranch_vccnz .LBB0_586
	global_load_dword v0, v15, s[26:27] offset:224
	s_waitcnt vmcnt(0)
	v_pk_mul_f32 v[4:5], v[4:5], v[0:1] op_sel_hi:[1,0]
	v_pk_mul_f32 v[2:3], v[2:3], v[0:1] op_sel_hi:[1,0]

.LBB0_588:
	s_andn2_b64 vcc, exec, s[10:11]
	s_cbranch_vccnz .LBB0_606
	s_movk_i32 s4, 0xc8
	v_readlane_b32 s12, v250, 57
	v_readlane_b32 s13, v250, 58
	s_load_dwordx2 s[4:5], s[12:13], s4 offset:0x0
	s_movk_i32 s10, 0xc0
	s_load_dwordx2 s[10:11], s[12:13], s10 offset:0x0
	s_mul_i32 s12, s52, 0xb00000
	s_waitcnt lgkmcnt(0)
	s_add_u32 s12, s4, s12
	s_addc_u32 s13, s5, 0
	v_readlane_b32 s4, v249, 9
	v_readlane_b32 s5, v249, 10
	s_lshl_b64 s[4:5], s[4:5], 2
	s_add_u32 s26, s10, s4
	s_addc_u32 s27, s11, s5
	s_add_i32 s4, s31, 0xfa80
	s_and_b32 s5, s4, 0xffff
	s_mul_i32 s5, s5, 0xba2f
	s_lshr_b32 s18, s5, 16
	s_lshr_b32 s5, s5, 22
	s_mulk_i32 s5, 0x58
	s_sub_i32 s4, s4, s5
	s_lshl_b32 s4, s4, 5
	v_and_b32_e32 v12, 7, v8
	s_and_b32 s4, s4, 0xffe0
	v_lshlrev_b32_e32 v11, 2, v12
	v_or_b32_e32 v0, s4, v11
	s_and_b32 s5, s18, 0xffc0
	v_lshlrev_b32_e32 v0, 2, v0
	v_lshrrev_b32_e32 v9, 3, v10
	v_lshl_add_u64 v[6:7], s[12:13], 0, v[0:1]
	v_or_b32_e32 v0, s5, v9
	s_movk_i32 s12, 0x2c00
	v_mad_u64_u32 v[2:3], s[12:13], v0, s12, v[6:7]
	v_mov_b32_e32 v68, 0x16000
	v_mov_b32_e32 v69, 0
	v_lshl_add_u64 v[70:71], v[2:3], 0, v[68:69]
	global_load_dwordx4 v[40:43], v[70:71], off
	v_lshl_add_u64 v[70:71], v[70:71], 0, v[68:69]
	global_load_dwordx4 v[44:47], v[70:71], off
	v_lshl_add_u64 v[70:71], v[70:71], 0, v[68:69]
	global_load_dwordx4 v[48:51], v[70:71], off
	v_lshl_add_u64 v[70:71], v[70:71], 0, v[68:69]
	global_load_dwordx4 v[52:55], v[70:71], off
	v_lshl_add_u64 v[70:71], v[70:71], 0, v[68:69]
	global_load_dwordx4 v[56:59], v[70:71], off
	v_lshl_add_u64 v[70:71], v[70:71], 0, v[68:69]
	global_load_dwordx4 v[60:63], v[70:71], off
	v_lshl_add_u64 v[70:71], v[70:71], 0, v[68:69]
	global_load_dwordx4 v[64:67], v[70:71], off
	global_load_dwordx4 v[2:5], v[2:3], off
	s_cmp_lg_u64 s[10:11], 0
	s_cselect_b64 s[28:29], -1, 0
	s_cmp_eq_u64 s[10:11], 0
	s_cbranch_scc1 .LBB0_591
	v_lshlrev_b32_e32 v0, 2, v0
	global_load_dword v72, v0, s[26:27] offset:128
	global_load_dword v0, v0, s[26:27]
	s_waitcnt vmcnt(0)
	v_pk_mul_f32 v[4:5], v[4:5], v[0:1] op_sel_hi:[1,0]
	v_pk_mul_f32 v[2:3], v[2:3], v[0:1] op_sel_hi:[1,0]
.LBB0_591:
	v_lshl_add_u32 v13, v11, 2, s30
	s_movk_i32 s10, 0x84
	v_mad_u32_u24 v0, v9, s10, v13
	v_or_b32_e32 v11, 8, v9
	s_waitcnt vmcnt(0)
	ds_write2_b32 v0, v2, v3 offset1:1
	ds_write2_b32 v0, v4, v5 offset0:2 offset1:3
	v_or_b32_e32 v0, s5, v11
	s_movk_i32 s10, 0x2c00
	v_mad_u64_u32 v[2:3], s[10:11], v0, s10, v[6:7]
	v_mov_b64_e32 v[2:3], v[40:41]
	v_mov_b64_e32 v[4:5], v[42:43]
	v_cndmask_b32_e64 v0, 0, 1, s[28:29]
	v_cmp_ne_u32_e64 s[10:11], 1, v0
	s_andn2_b64 vcc, exec, s[28:29]
	v_add_lshl_u32 v0, v9, s5, 2
	s_cbranch_vccnz .LBB0_593
	global_load_dword v14, v0, s[26:27] offset:32
	s_waitcnt vmcnt(0)
	v_pk_mul_f32 v[4:5], v[4:5], v[14:15] op_sel_hi:[1,0]
	v_pk_mul_f32 v[2:3], v[2:3], v[14:15] op_sel_hi:[1,0]
.LBB0_593:
	v_mul_u32_u24_e32 v14, 0x84, v9
	v_add_u32_e32 v15, v14, v13
	v_add_u32_e32 v13, 0x420, v15
	s_waitcnt vmcnt(0)
	ds_write2_b32 v13, v2, v3 offset1:1
	v_add_u32_e32 v2, 0x428, v15
	v_or_b32_e32 v13, 16, v9
	ds_write2_b32 v2, v4, v5 offset1:1
	v_or_b32_e32 v2, s5, v13
	s_movk_i32 s12, 0x2c00
	v_mad_u64_u32 v[2:3], s[12:13], v2, s12, v[6:7]
	v_mov_b64_e32 v[2:3], v[44:45]
	v_mov_b64_e32 v[4:5], v[46:47]
	s_and_b64 vcc, exec, s[10:11]
	s_cbranch_vccnz .LBB0_595
	global_load_dword v14, v0, s[26:27] offset:64
	s_waitcnt vmcnt(0)
	v_pk_mul_f32 v[4:5], v[4:5], v[14:15] op_sel_hi:[1,0]
	v_pk_mul_f32 v[2:3], v[2:3], v[14:15] op_sel_hi:[1,0]
.LBB0_595:
	v_add_u32_e32 v14, 0x840, v15
	s_waitcnt vmcnt(0)
	ds_write2_b32 v14, v2, v3 offset1:1
	v_add_u32_e32 v2, 0x848, v15
	v_or_b32_e32 v14, 24, v9
	ds_write2_b32 v2, v4, v5 offset1:1
	v_or_b32_e32 v2, s5, v14
	s_movk_i32 s12, 0x2c00
	v_mad_u64_u32 v[2:3], s[12:13], v2, s12, v[6:7]
	v_mov_b64_e32 v[2:3], v[48:49]
	v_mov_b64_e32 v[4:5], v[50:51]
	s_and_b64 vcc, exec, s[10:11]
	s_cbranch_vccnz .LBB0_597
	global_load_dword v16, v0, s[26:27] offset:96
	s_waitcnt vmcnt(0)
	v_pk_mul_f32 v[4:5], v[4:5], v[16:17] op_sel_hi:[1,0]
	v_pk_mul_f32 v[2:3], v[2:3], v[16:17] op_sel_hi:[1,0]
.LBB0_597:
	v_add_u32_e32 v16, 0xc60, v15
	s_waitcnt vmcnt(0)
	ds_write2_b32 v16, v2, v3 offset1:1
	v_add_u32_e32 v2, 0xc68, v15
	ds_write2_b32 v2, v4, v5 offset1:1
	v_or3_b32 v2, v9, s5, 32
	s_movk_i32 s12, 0x2c00
	v_mad_u64_u32 v[2:3], s[12:13], v2, s12, v[6:7]
	v_mov_b64_e32 v[2:3], v[52:53]
	v_mov_b64_e32 v[4:5], v[54:55]
	s_and_b64 vcc, exec, s[10:11]
	s_cbranch_vccnz .LBB0_599
	global_load_dword v16, v0, s[26:27] offset:128
	s_waitcnt vmcnt(0)
	v_pk_mul_f32 v[4:5], v[4:5], v[16:17] op_sel_hi:[1,0]
	v_pk_mul_f32 v[2:3], v[2:3], v[16:17] op_sel_hi:[1,0]
.LBB0_599:
	v_add_u32_e32 v16, 0x1080, v15
	s_waitcnt vmcnt(0)
	ds_write2_b32 v16, v2, v3 offset1:1
	v_add_u32_e32 v2, 0x1088, v15
	ds_write2_b32 v2, v4, v5 offset1:1
	v_or3_b32 v2, v9, s5, 40
	s_movk_i32 s12, 0x2c00
	v_mad_u64_u32 v[2:3], s[12:13], v2, s12, v[6:7]
	v_mov_b64_e32 v[2:3], v[56:57]
	v_mov_b64_e32 v[4:5], v[58:59]
	s_and_b64 vcc, exec, s[10:11]
	s_cbranch_vccnz .LBB0_601
	global_load_dword v16, v0, s[26:27] offset:160
	s_waitcnt vmcnt(0)
	v_pk_mul_f32 v[4:5], v[4:5], v[16:17] op_sel_hi:[1,0]
	v_pk_mul_f32 v[2:3], v[2:3], v[16:17] op_sel_hi:[1,0]
.LBB0_601:
	v_add_u32_e32 v16, 0x14a0, v15
	s_waitcnt vmcnt(0)
	ds_write2_b32 v16, v2, v3 offset1:1
	v_add_u32_e32 v2, 0x14a8, v15
	ds_write2_b32 v2, v4, v5 offset1:1
	v_or3_b32 v2, v9, s5, 48
	s_movk_i32 s12, 0x2c00
	v_mad_u64_u32 v[2:3], s[12:13], v2, s12, v[6:7]
	v_mov_b64_e32 v[2:3], v[60:61]
	v_mov_b64_e32 v[4:5], v[62:63]
	s_and_b64 vcc, exec, s[10:11]
	s_cbranch_vccnz .LBB0_603
	global_load_dword v16, v0, s[26:27] offset:192
	s_waitcnt vmcnt(0)
	v_pk_mul_f32 v[4:5], v[4:5], v[16:17] op_sel_hi:[1,0]
	v_pk_mul_f32 v[2:3], v[2:3], v[16:17] op_sel_hi:[1,0]
.LBB0_603:
	v_add_u32_e32 v16, 0x18c0, v15
	s_waitcnt vmcnt(0)
	ds_write2_b32 v16, v2, v3 offset1:1
	v_add_u32_e32 v2, 0x18c8, v15
	ds_write2_b32 v2, v4, v5 offset1:1
	v_or3_b32 v2, v9, s5, 56
	s_movk_i32 s12, 0x2c00
	v_mad_u64_u32 v[2:3], s[12:13], v2, s12, v[6:7]
	v_mov_b64_e32 v[2:3], v[64:65]
	v_mov_b64_e32 v[4:5], v[66:67]
	s_and_b64 vcc, exec, s[10:11]
	s_cbranch_vccnz .LBB0_605
	global_load_dword v0, v0, s[26:27] offset:224
	s_waitcnt vmcnt(0)
	v_pk_mul_f32 v[4:5], v[4:5], v[0:1] op_sel_hi:[1,0]
	v_pk_mul_f32 v[2:3], v[2:3], v[0:1] op_sel_hi:[1,0]

.LBB0_607:
	s_andn2_b64 vcc, exec, s[10:11]
	s_cbranch_vccnz .LBB0_609
	s_movk_i32 s4, 0xb8
	v_readlane_b32 s10, v250, 57
	v_readlane_b32 s11, v250, 58
	s_load_dwordx2 s[4:5], s[10:11], s4 offset:0x0
	v_readlane_b32 s10, v249, 15
	v_and_b32_e32 v3, 7, v8
	v_lshlrev_b32_e32 v2, 4, v3
	v_lshrrev_b32_e32 v9, 3, v10
	s_waitcnt lgkmcnt(0)
	s_add_u32 s10, s4, s10
	s_addc_u32 s11, s5, 0
	s_lshl_b32 s4, s31, 1
	s_add_i32 s4, s4, 0x1f900
	s_and_b32 s5, s4, 0x1ffc0
	s_lshl_b32 s4, s31, 5
	s_and_b32 s4, s4, 0x3e0
	v_lshl_or_b32 v0, s4, 2, v2
	v_lshl_add_u64 v[12:13], s[10:11], 0, v[0:1]
	v_or_b32_e32 v0, s5, v9
	v_lshlrev_b32_e32 v0, 12, v0
	v_lshl_add_u64 v[4:5], v[12:13], 0, v[0:1]
	v_mov_b32_e32 v68, 0x8000
	v_mov_b32_e32 v69, 0
	v_lshl_add_u64 v[70:71], v[4:5], 0, v[68:69]
	global_load_dwordx4 v[40:43], v[70:71], off
	v_lshl_add_u64 v[70:71], v[70:71], 0, v[68:69]
	global_load_dwordx4 v[44:47], v[70:71], off
	v_lshl_add_u64 v[70:71], v[70:71], 0, v[68:69]
	global_load_dwordx4 v[48:51], v[70:71], off
	v_lshl_add_u64 v[70:71], v[70:71], 0, v[68:69]
	global_load_dwordx4 v[52:55], v[70:71], off
	v_lshl_add_u64 v[70:71], v[70:71], 0, v[68:69]
	global_load_dwordx4 v[56:59], v[70:71], off
	v_lshl_add_u64 v[70:71], v[70:71], 0, v[68:69]
	global_load_dwordx4 v[60:63], v[70:71], off
	v_lshl_add_u64 v[70:71], v[70:71], 0, v[68:69]
	global_load_dwordx4 v[64:67], v[70:71], off
	global_load_dwordx4 v[4:7], v[4:5], off
	v_mul_u32_u24_e32 v11, 0x84, v9
	v_add3_u32 v11, s30, v2, v11
	v_or_b32_e32 v30, 8, v9
	v_add_u32_e32 v14, 0x420, v11
	v_or_b32_e32 v31, 16, v9
	v_or_b32_e32 v32, 24, v9
	v_readlane_b32 s10, v249, 17
	s_waitcnt vmcnt(0)
	ds_write2_b32 v11, v4, v5 offset1:1
	ds_write2_b32 v11, v6, v7 offset0:2 offset1:3
	v_or_b32_e32 v4, s5, v30
	v_lshlrev_b32_e32 v4, 12, v4
	v_mov_b32_e32 v5, v1
	v_lshl_add_u64 v[4:5], v[12:13], 0, v[4:5]
	v_mov_b64_e32 v[4:5], v[40:41]
	v_mov_b64_e32 v[6:7], v[42:43]
	s_waitcnt vmcnt(0)
	ds_write2_b32 v14, v4, v5 offset1:1
	v_add_u32_e32 v4, 0x428, v11
	ds_write2_b32 v4, v6, v7 offset1:1
	v_or_b32_e32 v4, s5, v31
	v_lshlrev_b32_e32 v4, 12, v4
	v_mov_b32_e32 v5, v1
	v_lshl_add_u64 v[4:5], v[12:13], 0, v[4:5]
	v_mov_b64_e32 v[4:5], v[44:45]
	v_mov_b64_e32 v[6:7], v[46:47]
	v_add_u32_e32 v14, 0x840, v11
	s_waitcnt vmcnt(0)
	ds_write2_b32 v14, v4, v5 offset1:1
	v_add_u32_e32 v4, 0x848, v11
	ds_write2_b32 v4, v6, v7 offset1:1
	v_or_b32_e32 v4, s5, v32
	v_lshlrev_b32_e32 v4, 12, v4
	v_mov_b32_e32 v5, v1
	v_lshl_add_u64 v[4:5], v[12:13], 0, v[4:5]
	v_mov_b64_e32 v[4:5], v[48:49]
	v_mov_b64_e32 v[6:7], v[50:51]
	v_add_u32_e32 v14, 0xc60, v11
	s_lshl_b32 s5, s5, 1
	s_add_u32 s10, s10, s5
	v_readlane_b32 s5, v249, 19
	s_addc_u32 s11, s5, 0
	s_waitcnt vmcnt(0)
	ds_write2_b32 v14, v4, v5 offset1:1
	v_add_u32_e32 v4, 0xc68, v11
	ds_write2_b32 v4, v6, v7 offset1:1
	v_or_b32_e32 v4, 0x20000, v0
	v_mov_b32_e32 v5, v1
	v_lshl_add_u64 v[4:5], v[12:13], 0, v[4:5]
	v_mov_b64_e32 v[4:5], v[52:53]
	v_mov_b64_e32 v[6:7], v[54:55]
	v_add_u32_e32 v14, 0x1080, v11
	s_waitcnt vmcnt(0)
	ds_write2_b32 v14, v4, v5 offset1:1
	v_add_u32_e32 v4, 0x1088, v11
	ds_write2_b32 v4, v6, v7 offset1:1
	v_or_b32_e32 v4, 0x28000, v0
	v_mov_b32_e32 v5, v1
	v_lshl_add_u64 v[4:5], v[12:13], 0, v[4:5]
	v_mov_b64_e32 v[4:5], v[56:57]
	v_mov_b64_e32 v[6:7], v[58:59]
	v_add_u32_e32 v14, 0x14a0, v11
	s_waitcnt vmcnt(0)
	ds_write2_b32 v14, v4, v5 offset1:1
	v_add_u32_e32 v4, 0x14a8, v11
	ds_write2_b32 v4, v6, v7 offset1:1
	v_or_b32_e32 v4, 0x30000, v0
	v_mov_b32_e32 v5, v1
	v_lshl_add_u64 v[4:5], v[12:13], 0, v[4:5]
	v_mov_b64_e32 v[4:5], v[60:61]
	v_mov_b64_e32 v[6:7], v[62:63]
	v_add_u32_e32 v14, 0x18c0, v11
	v_or_b32_e32 v0, 0x38000, v0
	s_waitcnt vmcnt(0)
	ds_write2_b32 v14, v4, v5 offset1:1
	v_add_u32_e32 v4, 0x18c8, v11
	ds_write2_b32 v4, v6, v7 offset1:1
	v_lshl_add_u64 v[4:5], v[12:13], 0, v[0:1]
	v_mov_b64_e32 v[4:5], v[64:65]
	v_mov_b64_e32 v[6:7], v[66:67]
	v_add_u32_e32 v0, 0x1ce0, v11
	s_waitcnt vmcnt(0)
	ds_write2_b32 v0, v4, v5 offset1:1
	v_add_u32_e32 v0, 0x1ce8, v11
	ds_write2_b32 v0, v6, v7 offset1:1
	v_mul_u32_u24_e32 v0, 0x420, v3
	v_lshlrev_b32_e32 v4, 2, v9
	s_waitcnt lgkmcnt(0)
	v_or_b32_e32 v11, s4, v9
	v_add3_u32 v9, s30, v0, v4
	ds_read2_b32 v[12:13], v9 offset0:198 offset1:206
	ds_read2_b32 v[14:15], v9 offset0:231 offset1:239
	ds_read2_b32 v[16:17], v9 offset0:132 offset1:140
	ds_read2_b32 v[18:19], v9 offset0:165 offset1:173
	ds_read2_b32 v[20:21], v9 offset0:66 offset1:74
	ds_read2_b32 v[22:23], v9 offset0:99 offset1:107
	ds_read2_b32 v[24:25], v9 offset0:33 offset1:41
	ds_read2_b32 v[26:27], v9 offset1:8
	v_mov_b32_e32 v3, v1
	v_lshl_add_u64 v[2:3], s[10:11], 0, v[2:3]
	v_lshlrev_b32_e32 v0, 11, v11
	v_lshl_add_u64 v[28:29], v[2:3], 0, v[0:1]
	v_or_b32_e32 v0, s4, v30
	s_waitcnt lgkmcnt(6)
	v_cvt_pk_bf16_f32 v7, v12, v14
	s_waitcnt lgkmcnt(4)
	v_cvt_pk_bf16_f32 v6, v16, v18
	s_waitcnt lgkmcnt(2)
	v_cvt_pk_bf16_f32 v5, v20, v22
	s_waitcnt lgkmcnt(0)
	v_cvt_pk_bf16_f32 v4, v26, v24
	v_lshlrev_b32_e32 v0, 11, v0
	global_store_dwordx4 v[28:29], v[4:7], off
	s_nop 1
	v_cvt_pk_bf16_f32 v7, v13, v15
	v_cvt_pk_bf16_f32 v6, v17, v19
	v_cvt_pk_bf16_f32 v5, v21, v23
	v_cvt_pk_bf16_f32 v4, v27, v25
	v_lshl_add_u64 v[12:13], v[2:3], 0, v[0:1]
	global_store_dwordx4 v[12:13], v[4:7], off
	ds_read2_b32 v[12:13], v9 offset0:214 offset1:222
	ds_read2_b32 v[14:15], v9 offset0:247 offset1:255
	ds_read2_b32 v[16:17], v9 offset0:148 offset1:156
	ds_read2_b32 v[18:19], v9 offset0:181 offset1:189
	ds_read2_b32 v[20:21], v9 offset0:82 offset1:90
	ds_read2_b32 v[22:23], v9 offset0:115 offset1:123
	ds_read2_b32 v[24:25], v9 offset0:49 offset1:57
	ds_read2_b32 v[26:27], v9 offset0:16 offset1:24
	v_or_b32_e32 v0, s4, v31
	v_lshlrev_b32_e32 v0, 11, v0
	v_lshl_add_u64 v[28:29], v[2:3], 0, v[0:1]
	v_or_b32_e32 v0, s4, v32
	s_waitcnt lgkmcnt(6)
	v_cvt_pk_bf16_f32 v7, v12, v14
	s_waitcnt lgkmcnt(4)
	v_cvt_pk_bf16_f32 v6, v16, v18
	s_waitcnt lgkmcnt(2)
	v_cvt_pk_bf16_f32 v5, v20, v22
	s_waitcnt lgkmcnt(0)
	v_cvt_pk_bf16_f32 v4, v26, v24
	v_lshlrev_b32_e32 v0, 11, v0
	global_store_dwordx4 v[28:29], v[4:7], off
	v_lshl_add_u64 v[2:3], v[2:3], 0, v[0:1]
	s_nop 0
	v_cvt_pk_bf16_f32 v7, v13, v15
	v_cvt_pk_bf16_f32 v6, v17, v19
	v_cvt_pk_bf16_f32 v5, v21, v23
	v_cvt_pk_bf16_f32 v4, v27, v25
	global_store_dwordx4 v[2:3], v[4:7], off
	s_waitcnt lgkmcnt(0)

.LBB0_610:
	s_andn2_b64 vcc, exec, s[10:11]
	s_cbranch_vccnz .LBB0_612
	s_movk_i32 s4, 0xb0
	v_readlane_b32 s10, v250, 57
	v_readlane_b32 s11, v250, 58
	s_load_dwordx2 s[4:5], s[10:11], s4 offset:0x0
	v_readlane_b32 s10, v249, 21
	v_and_b32_e32 v3, 7, v8
	v_lshlrev_b32_e32 v2, 4, v3
	v_lshrrev_b32_e32 v9, 3, v10
	s_waitcnt lgkmcnt(0)
	s_add_u32 s10, s4, s10
	s_addc_u32 s11, s5, 0
	s_lshl_b32 s4, s31, 1
	s_and_b32 s5, s4, 0x1c0
	s_lshl_b32 s4, s31, 5
	s_and_b32 s4, s4, 0x3e0
	v_lshl_or_b32 v0, s4, 2, v2
	v_lshl_add_u64 v[12:13], s[10:11], 0, v[0:1]
	v_or_b32_e32 v0, s5, v9
	v_lshlrev_b32_e32 v0, 12, v0
	v_lshl_add_u64 v[4:5], v[12:13], 0, v[0:1]
	v_mov_b32_e32 v68, 0x8000
	v_mov_b32_e32 v69, 0
	v_lshl_add_u64 v[70:71], v[4:5], 0, v[68:69]
	global_load_dwordx4 v[40:43], v[70:71], off
	v_lshl_add_u64 v[70:71], v[70:71], 0, v[68:69]
	global_load_dwordx4 v[44:47], v[70:71], off
	v_lshl_add_u64 v[70:71], v[70:71], 0, v[68:69]
	global_load_dwordx4 v[48:51], v[70:71], off
	v_lshl_add_u64 v[70:71], v[70:71], 0, v[68:69]
	global_load_dwordx4 v[52:55], v[70:71], off
	v_lshl_add_u64 v[70:71], v[70:71], 0, v[68:69]
	global_load_dwordx4 v[56:59], v[70:71], off
	v_lshl_add_u64 v[70:71], v[70:71], 0, v[68:69]
	global_load_dwordx4 v[60:63], v[70:71], off
	v_lshl_add_u64 v[70:71], v[70:71], 0, v[68:69]
	global_load_dwordx4 v[64:67], v[70:71], off
	global_load_dwordx4 v[4:7], v[4:5], off
	v_mul_u32_u24_e32 v11, 0x84, v9
	v_add3_u32 v11, s30, v2, v11
	v_or_b32_e32 v30, 8, v9
	v_add_u32_e32 v14, 0x420, v11
	v_or_b32_e32 v31, 16, v9
	v_or_b32_e32 v32, 24, v9
	v_readlane_b32 s10, v249, 23
	s_waitcnt vmcnt(0)
	ds_write2_b32 v11, v4, v5 offset1:1
	ds_write2_b32 v11, v6, v7 offset0:2 offset1:3
	v_or_b32_e32 v4, s5, v30
	v_lshlrev_b32_e32 v4, 12, v4
	v_mov_b32_e32 v5, v1
	v_lshl_add_u64 v[4:5], v[12:13], 0, v[4:5]
	v_mov_b64_e32 v[4:5], v[40:41]
	v_mov_b64_e32 v[6:7], v[42:43]
	s_waitcnt vmcnt(0)
	ds_write2_b32 v14, v4, v5 offset1:1
	v_add_u32_e32 v4, 0x428, v11
	ds_write2_b32 v4, v6, v7 offset1:1
	v_or_b32_e32 v4, s5, v31
	v_lshlrev_b32_e32 v4, 12, v4
	v_mov_b32_e32 v5, v1
	v_lshl_add_u64 v[4:5], v[12:13], 0, v[4:5]
	v_mov_b64_e32 v[4:5], v[44:45]
	v_mov_b64_e32 v[6:7], v[46:47]
	v_add_u32_e32 v14, 0x840, v11
	s_waitcnt vmcnt(0)
	ds_write2_b32 v14, v4, v5 offset1:1
	v_add_u32_e32 v4, 0x848, v11
	ds_write2_b32 v4, v6, v7 offset1:1
	v_or_b32_e32 v4, s5, v32
	v_lshlrev_b32_e32 v4, 12, v4
	v_mov_b32_e32 v5, v1
	v_lshl_add_u64 v[4:5], v[12:13], 0, v[4:5]
	v_mov_b64_e32 v[4:5], v[48:49]
	v_mov_b64_e32 v[6:7], v[50:51]
	v_add_u32_e32 v14, 0xc60, v11
	s_lshl_b32 s5, s5, 1
	s_add_u32 s10, s10, s5
	v_readlane_b32 s5, v249, 25
	s_addc_u32 s11, s5, 0
	s_waitcnt vmcnt(0)
	ds_write2_b32 v14, v4, v5 offset1:1
	v_add_u32_e32 v4, 0xc68, v11
	ds_write2_b32 v4, v6, v7 offset1:1
	v_or_b32_e32 v4, 0x20000, v0
	v_mov_b32_e32 v5, v1
	v_lshl_add_u64 v[4:5], v[12:13], 0, v[4:5]
	v_mov_b64_e32 v[4:5], v[52:53]
	v_mov_b64_e32 v[6:7], v[54:55]
	v_add_u32_e32 v14, 0x1080, v11
	s_waitcnt vmcnt(0)
	ds_write2_b32 v14, v4, v5 offset1:1
	v_add_u32_e32 v4, 0x1088, v11
	ds_write2_b32 v4, v6, v7 offset1:1
	v_or_b32_e32 v4, 0x28000, v0
	v_mov_b32_e32 v5, v1
	v_lshl_add_u64 v[4:5], v[12:13], 0, v[4:5]
	v_mov_b64_e32 v[4:5], v[56:57]
	v_mov_b64_e32 v[6:7], v[58:59]
	v_add_u32_e32 v14, 0x14a0, v11
	s_waitcnt vmcnt(0)
	ds_write2_b32 v14, v4, v5 offset1:1
	v_add_u32_e32 v4, 0x14a8, v11
	ds_write2_b32 v4, v6, v7 offset1:1
	v_or_b32_e32 v4, 0x30000, v0
	v_mov_b32_e32 v5, v1
	v_lshl_add_u64 v[4:5], v[12:13], 0, v[4:5]
	v_mov_b64_e32 v[4:5], v[60:61]
	v_mov_b64_e32 v[6:7], v[62:63]
	v_add_u32_e32 v14, 0x18c0, v11
	v_or_b32_e32 v0, 0x38000, v0
	s_waitcnt vmcnt(0)
	ds_write2_b32 v14, v4, v5 offset1:1
	v_add_u32_e32 v4, 0x18c8, v11
	ds_write2_b32 v4, v6, v7 offset1:1
	v_lshl_add_u64 v[4:5], v[12:13], 0, v[0:1]
	v_mov_b64_e32 v[4:5], v[64:65]
	v_mov_b64_e32 v[6:7], v[66:67]
	v_add_u32_e32 v0, 0x1ce0, v11
	s_waitcnt vmcnt(0)
	ds_write2_b32 v0, v4, v5 offset1:1
	v_add_u32_e32 v0, 0x1ce8, v11
	ds_write2_b32 v0, v6, v7 offset1:1
	v_mul_u32_u24_e32 v0, 0x420, v3
	v_lshlrev_b32_e32 v4, 2, v9
	s_waitcnt lgkmcnt(0)
	v_or_b32_e32 v11, s4, v9
	v_add3_u32 v9, s30, v0, v4
	ds_read2_b32 v[12:13], v9 offset0:198 offset1:206
	ds_read2_b32 v[14:15], v9 offset0:231 offset1:239
	ds_read2_b32 v[16:17], v9 offset0:132 offset1:140
	ds_read2_b32 v[18:19], v9 offset0:165 offset1:173
	ds_read2_b32 v[20:21], v9 offset0:66 offset1:74
	ds_read2_b32 v[22:23], v9 offset0:99 offset1:107
	ds_read2_b32 v[24:25], v9 offset0:33 offset1:41
	ds_read2_b32 v[26:27], v9 offset1:8
	v_mov_b32_e32 v3, v1
	v_lshl_add_u64 v[2:3], s[10:11], 0, v[2:3]
	v_lshlrev_b32_e32 v0, 9, v11
	v_lshl_add_u64 v[28:29], v[2:3], 0, v[0:1]
	v_or_b32_e32 v0, s4, v30
	s_waitcnt lgkmcnt(6)
	v_cvt_pk_bf16_f32 v7, v12, v14
	s_waitcnt lgkmcnt(4)
	v_cvt_pk_bf16_f32 v6, v16, v18
	s_waitcnt lgkmcnt(2)
	v_cvt_pk_bf16_f32 v5, v20, v22
	s_waitcnt lgkmcnt(0)
	v_cvt_pk_bf16_f32 v4, v26, v24
	v_lshlrev_b32_e32 v0, 9, v0
	global_store_dwordx4 v[28:29], v[4:7], off
	s_nop 1
	v_cvt_pk_bf16_f32 v7, v13, v15
	v_cvt_pk_bf16_f32 v6, v17, v19
	v_cvt_pk_bf16_f32 v5, v21, v23
	v_cvt_pk_bf16_f32 v4, v27, v25
	v_lshl_add_u64 v[12:13], v[2:3], 0, v[0:1]
	global_store_dwordx4 v[12:13], v[4:7], off
	ds_read2_b32 v[12:13], v9 offset0:214 offset1:222
	ds_read2_b32 v[14:15], v9 offset0:247 offset1:255
	ds_read2_b32 v[16:17], v9 offset0:148 offset1:156
	ds_read2_b32 v[18:19], v9 offset0:181 offset1:189
	ds_read2_b32 v[20:21], v9 offset0:82 offset1:90
	ds_read2_b32 v[22:23], v9 offset0:115 offset1:123
	ds_read2_b32 v[24:25], v9 offset0:49 offset1:57
	ds_read2_b32 v[26:27], v9 offset0:16 offset1:24
	v_or_b32_e32 v0, s4, v31
	v_lshlrev_b32_e32 v0, 9, v0
	v_lshl_add_u64 v[28:29], v[2:3], 0, v[0:1]
	v_or_b32_e32 v0, s4, v32
	s_waitcnt lgkmcnt(6)
	v_cvt_pk_bf16_f32 v7, v12, v14
	s_waitcnt lgkmcnt(4)
	v_cvt_pk_bf16_f32 v6, v16, v18
	s_waitcnt lgkmcnt(2)
	v_cvt_pk_bf16_f32 v5, v20, v22
	s_waitcnt lgkmcnt(0)
	v_cvt_pk_bf16_f32 v4, v26, v24
	v_lshlrev_b32_e32 v0, 9, v0
	global_store_dwordx4 v[28:29], v[4:7], off
	v_lshl_add_u64 v[2:3], v[2:3], 0, v[0:1]
	s_nop 0
	v_cvt_pk_bf16_f32 v7, v13, v15
	v_cvt_pk_bf16_f32 v6, v17, v19
	v_cvt_pk_bf16_f32 v5, v21, v23
	v_cvt_pk_bf16_f32 v4, v27, v25
	global_store_dwordx4 v[2:3], v[4:7], off
	s_waitcnt lgkmcnt(0)

.LBB0_613:
	s_andn2_b64 vcc, exec, s[10:11]
	s_cbranch_vccnz .LBB0_615
	s_movk_i32 s4, 0xa8
	v_readlane_b32 s10, v250, 57
	v_readlane_b32 s11, v250, 58
	s_load_dwordx2 s[4:5], s[10:11], s4 offset:0x0
	s_mul_i32 s10, s52, 0x300000
	v_and_b32_e32 v3, 7, v8
	v_lshlrev_b32_e32 v2, 4, v3
	v_lshrrev_b32_e32 v9, 3, v10
	s_waitcnt lgkmcnt(0)
	s_add_u32 s10, s4, s10
	s_addc_u32 s11, s5, 0
	s_lshl_b32 s4, s31, 1
	s_add_i32 s4, s4, 0x1fd00
	s_and_b32 s5, s4, 0x1ffc0
	s_lshl_b32 s4, s31, 5
	s_and_b32 s4, s4, 0x3e0
	v_lshl_or_b32 v0, s4, 2, v2
	v_lshl_add_u64 v[12:13], s[10:11], 0, v[0:1]
	v_or_b32_e32 v0, s5, v9
	v_lshlrev_b32_e32 v0, 12, v0
	v_lshl_add_u64 v[4:5], v[12:13], 0, v[0:1]
	v_mov_b32_e32 v68, 0x8000
	v_mov_b32_e32 v69, 0
	v_lshl_add_u64 v[70:71], v[4:5], 0, v[68:69]
	global_load_dwordx4 v[40:43], v[70:71], off
	v_lshl_add_u64 v[70:71], v[70:71], 0, v[68:69]
	global_load_dwordx4 v[44:47], v[70:71], off
	v_lshl_add_u64 v[70:71], v[70:71], 0, v[68:69]
	global_load_dwordx4 v[48:51], v[70:71], off
	v_lshl_add_u64 v[70:71], v[70:71], 0, v[68:69]
	global_load_dwordx4 v[52:55], v[70:71], off
	v_lshl_add_u64 v[70:71], v[70:71], 0, v[68:69]
	global_load_dwordx4 v[56:59], v[70:71], off
	v_lshl_add_u64 v[70:71], v[70:71], 0, v[68:69]
	global_load_dwordx4 v[60:63], v[70:71], off
	v_lshl_add_u64 v[70:71], v[70:71], 0, v[68:69]
	global_load_dwordx4 v[64:67], v[70:71], off
	global_load_dwordx4 v[4:7], v[4:5], off
	v_mul_u32_u24_e32 v11, 0x84, v9
	v_add3_u32 v11, s30, v2, v11
	v_or_b32_e32 v30, 8, v9
	v_add_u32_e32 v14, 0x420, v11
	v_or_b32_e32 v31, 16, v9
	v_or_b32_e32 v32, 24, v9
	v_readlane_b32 s10, v249, 27
	s_waitcnt vmcnt(0)
	ds_write2_b32 v11, v4, v5 offset1:1
	ds_write2_b32 v11, v6, v7 offset0:2 offset1:3
	v_or_b32_e32 v4, s5, v30
	v_lshlrev_b32_e32 v4, 12, v4
	v_mov_b32_e32 v5, v1
	v_lshl_add_u64 v[4:5], v[12:13], 0, v[4:5]
	v_mov_b64_e32 v[4:5], v[40:41]
	v_mov_b64_e32 v[6:7], v[42:43]
	s_waitcnt vmcnt(0)
	ds_write2_b32 v14, v4, v5 offset1:1
	v_add_u32_e32 v4, 0x428, v11
	ds_write2_b32 v4, v6, v7 offset1:1
	v_or_b32_e32 v4, s5, v31
	v_lshlrev_b32_e32 v4, 12, v4
	v_mov_b32_e32 v5, v1
	v_lshl_add_u64 v[4:5], v[12:13], 0, v[4:5]
	v_mov_b64_e32 v[4:5], v[44:45]
	v_mov_b64_e32 v[6:7], v[46:47]
	v_add_u32_e32 v14, 0x840, v11
	s_waitcnt vmcnt(0)
	ds_write2_b32 v14, v4, v5 offset1:1
	v_add_u32_e32 v4, 0x848, v11
	ds_write2_b32 v4, v6, v7 offset1:1
	v_or_b32_e32 v4, s5, v32
	v_lshlrev_b32_e32 v4, 12, v4
	v_mov_b32_e32 v5, v1
	v_lshl_add_u64 v[4:5], v[12:13], 0, v[4:5]
	v_mov_b64_e32 v[4:5], v[48:49]
	v_mov_b64_e32 v[6:7], v[50:51]
	v_add_u32_e32 v14, 0xc60, v11
	s_lshl_b32 s5, s5, 1
	s_add_u32 s10, s10, s5
	v_readlane_b32 s5, v249, 28
	s_addc_u32 s11, s5, 0
	s_waitcnt vmcnt(0)
	ds_write2_b32 v14, v4, v5 offset1:1
	v_add_u32_e32 v4, 0xc68, v11
	ds_write2_b32 v4, v6, v7 offset1:1
	v_or_b32_e32 v4, 0x20000, v0
	v_mov_b32_e32 v5, v1
	v_lshl_add_u64 v[4:5], v[12:13], 0, v[4:5]
	v_mov_b64_e32 v[4:5], v[52:53]
	v_mov_b64_e32 v[6:7], v[54:55]
	v_add_u32_e32 v14, 0x1080, v11
	s_waitcnt vmcnt(0)
	ds_write2_b32 v14, v4, v5 offset1:1
	v_add_u32_e32 v4, 0x1088, v11
	ds_write2_b32 v4, v6, v7 offset1:1
	v_or_b32_e32 v4, 0x28000, v0
	v_mov_b32_e32 v5, v1
	v_lshl_add_u64 v[4:5], v[12:13], 0, v[4:5]
	v_mov_b64_e32 v[4:5], v[56:57]
	v_mov_b64_e32 v[6:7], v[58:59]
	v_add_u32_e32 v14, 0x14a0, v11
	s_waitcnt vmcnt(0)
	ds_write2_b32 v14, v4, v5 offset1:1
	v_add_u32_e32 v4, 0x14a8, v11
	ds_write2_b32 v4, v6, v7 offset1:1
	v_or_b32_e32 v4, 0x30000, v0
	v_mov_b32_e32 v5, v1
	v_lshl_add_u64 v[4:5], v[12:13], 0, v[4:5]
	v_mov_b64_e32 v[4:5], v[60:61]
	v_mov_b64_e32 v[6:7], v[62:63]
	v_add_u32_e32 v14, 0x18c0, v11
	v_or_b32_e32 v0, 0x38000, v0
	s_waitcnt vmcnt(0)
	ds_write2_b32 v14, v4, v5 offset1:1
	v_add_u32_e32 v4, 0x18c8, v11
	ds_write2_b32 v4, v6, v7 offset1:1
	v_lshl_add_u64 v[4:5], v[12:13], 0, v[0:1]
	v_mov_b64_e32 v[4:5], v[64:65]
	v_mov_b64_e32 v[6:7], v[66:67]
	v_add_u32_e32 v0, 0x1ce0, v11
	s_waitcnt vmcnt(0)
	ds_write2_b32 v0, v4, v5 offset1:1
	v_add_u32_e32 v0, 0x1ce8, v11
	ds_write2_b32 v0, v6, v7 offset1:1
	v_mul_u32_u24_e32 v0, 0x420, v3
	v_lshlrev_b32_e32 v4, 2, v9
	s_waitcnt lgkmcnt(0)
	v_or_b32_e32 v11, s4, v9
	v_add3_u32 v9, s30, v0, v4
	ds_read2_b32 v[12:13], v9 offset0:198 offset1:206
	ds_read2_b32 v[14:15], v9 offset0:231 offset1:239
	ds_read2_b32 v[16:17], v9 offset0:132 offset1:140
	ds_read2_b32 v[18:19], v9 offset0:165 offset1:173
	ds_read2_b32 v[20:21], v9 offset0:66 offset1:74
	ds_read2_b32 v[22:23], v9 offset0:99 offset1:107
	ds_read2_b32 v[24:25], v9 offset0:33 offset1:41
	ds_read2_b32 v[26:27], v9 offset1:8
	v_mov_b32_e32 v3, v1
	v_mul_u32_u24_e32 v0, 0x300, v11
	v_lshl_add_u64 v[2:3], s[10:11], 0, v[2:3]
	v_lshlrev_b32_e32 v0, 1, v0
	v_lshl_add_u64 v[28:29], v[2:3], 0, v[0:1]
	v_or_b32_e32 v0, s4, v30
	v_mul_u32_u24_e32 v0, 0x300, v0
	s_waitcnt lgkmcnt(6)
	v_cvt_pk_bf16_f32 v7, v12, v14
	s_waitcnt lgkmcnt(4)
	v_cvt_pk_bf16_f32 v6, v16, v18
	s_waitcnt lgkmcnt(2)
	v_cvt_pk_bf16_f32 v5, v20, v22
	s_waitcnt lgkmcnt(0)
	v_cvt_pk_bf16_f32 v4, v26, v24
	v_lshlrev_b32_e32 v0, 1, v0
	global_store_dwordx4 v[28:29], v[4:7], off
	s_nop 1
	v_cvt_pk_bf16_f32 v7, v13, v15
	v_cvt_pk_bf16_f32 v6, v17, v19
	v_cvt_pk_bf16_f32 v5, v21, v23
	v_cvt_pk_bf16_f32 v4, v27, v25
	v_lshl_add_u64 v[12:13], v[2:3], 0, v[0:1]
	global_store_dwordx4 v[12:13], v[4:7], off
	v_or_b32_e32 v0, s4, v31
	ds_read2_b32 v[12:13], v9 offset0:214 offset1:222
	ds_read2_b32 v[14:15], v9 offset0:247 offset1:255
	ds_read2_b32 v[16:17], v9 offset0:148 offset1:156
	ds_read2_b32 v[18:19], v9 offset0:181 offset1:189
	ds_read2_b32 v[20:21], v9 offset0:82 offset1:90
	ds_read2_b32 v[22:23], v9 offset0:115 offset1:123
	ds_read2_b32 v[24:25], v9 offset0:16 offset1:24
	ds_read2_b32 v[26:27], v9 offset0:49 offset1:57
	v_mul_u32_u24_e32 v0, 0x300, v0
	v_lshlrev_b32_e32 v0, 1, v0
	v_lshl_add_u64 v[28:29], v[2:3], 0, v[0:1]
	v_or_b32_e32 v0, s4, v32
	v_mul_u32_u24_e32 v0, 0x300, v0
	s_waitcnt lgkmcnt(6)
	v_cvt_pk_bf16_f32 v7, v12, v14
	s_waitcnt lgkmcnt(4)
	v_cvt_pk_bf16_f32 v6, v16, v18
	s_waitcnt lgkmcnt(2)
	v_cvt_pk_bf16_f32 v5, v20, v22
	s_waitcnt lgkmcnt(0)
	v_cvt_pk_bf16_f32 v4, v24, v26
	v_lshlrev_b32_e32 v0, 1, v0
	global_store_dwordx4 v[28:29], v[4:7], off
	v_lshl_add_u64 v[2:3], v[2:3], 0, v[0:1]
	s_nop 0
	v_cvt_pk_bf16_f32 v7, v13, v15
	v_cvt_pk_bf16_f32 v6, v17, v19
	v_cvt_pk_bf16_f32 v5, v21, v23
	v_cvt_pk_bf16_f32 v4, v25, v27
	global_store_dwordx4 v[2:3], v[4:7], off
	s_waitcnt lgkmcnt(0)

.LBB0_616:
	s_andn2_b64 vcc, exec, s[10:11]
	s_cbranch_vccnz .LBB0_642
	s_movk_i32 s4, 0xa0
	v_readlane_b32 s10, v250, 57
	v_readlane_b32 s11, v250, 58
	s_load_dwordx2 s[4:5], s[10:11], s4 offset:0x0
	s_mul_i32 s10, s52, 0x300000
	v_and_b32_e32 v0, 7, v8
	v_lshlrev_b32_e32 v3, 2, v0
	v_lshrrev_b32_e32 v13, 3, v10
	s_waitcnt lgkmcnt(0)
	s_add_u32 s12, s4, s10
	s_addc_u32 s13, s5, 0
	s_ashr_i32 s4, s31, 31
	s_lshr_b32 s4, s4, 27
	s_add_i32 s4, s31, s4
	s_and_b32 s5, s4, 0x7ffffe0
	s_lshl_b32 s4, s4, 1
	s_sub_i32 s5, s31, s5
	s_and_b32 s10, s4, 0xffffffc0
	s_lshl_b32 s4, s5, 5
	v_or_b32_e32 v2, s4, v3
	v_or_b32_e32 v4, 3, v2
	s_movk_i32 s5, 0x400
	v_cmp_gt_i32_e32 vcc, s5, v4
	v_mov_b32_e32 v6, 0
	v_mov_b32_e32 v7, 0
	v_cndmask_b32_e32 v4, 0, v2, vcc
	v_ashrrev_i32_e32 v5, 31, v4
	v_lshl_add_u64 v[8:9], v[4:5], 2, s[12:13]
	v_mov_b32_e32 v2, 0
	v_mov_b32_e32 v4, 0
	v_mov_b32_e32 v5, 0
	s_and_saveexec_b64 s[26:27], vcc
	s_cbranch_execz .LBB0_619
	v_or_b32_e32 v4, s10, v13
	v_ashrrev_i32_e32 v5, 31, v4
	v_lshlrev_b64 v[4:5], 12, v[4:5]
	v_lshl_add_u64 v[4:5], v[8:9], 0, v[4:5]
	v_mov_b32_e32 v68, 0x8000
	v_mov_b32_e32 v69, 0
	v_lshl_add_u64 v[70:71], v[4:5], 0, v[68:69]
	global_load_dwordx4 v[40:43], v[70:71], off
	v_lshl_add_u64 v[70:71], v[70:71], 0, v[68:69]
	global_load_dwordx4 v[44:47], v[70:71], off
	v_lshl_add_u64 v[70:71], v[70:71], 0, v[68:69]
	global_load_dwordx4 v[48:51], v[70:71], off
	v_lshl_add_u64 v[70:71], v[70:71], 0, v[68:69]
	global_load_dwordx4 v[52:55], v[70:71], off
	v_lshl_add_u64 v[70:71], v[70:71], 0, v[68:69]
	global_load_dwordx4 v[56:59], v[70:71], off
	v_lshl_add_u64 v[70:71], v[70:71], 0, v[68:69]
	global_load_dwordx4 v[60:63], v[70:71], off
	v_lshl_add_u64 v[70:71], v[70:71], 0, v[68:69]
	global_load_dwordx4 v[64:67], v[70:71], off
	global_load_dwordx4 v[4:7], v[4:5], off
.LBB0_619:
	s_or_b64 exec, exec, s[26:27]
	v_lshl_add_u32 v10, v3, 2, s30
	s_movk_i32 s5, 0x84
	v_mad_u32_u24 v3, v13, s5, v10
	s_waitcnt vmcnt(0)
	ds_write2_b32 v3, v4, v5 offset1:1
	ds_write2_b32 v3, v6, v7 offset0:2 offset1:3
	v_or_b32_e32 v12, 8, v13
	v_mov_b32_e32 v3, 0
	v_mov_b32_e32 v4, 0
	v_mov_b32_e32 v5, 0
	s_and_saveexec_b64 s[26:27], vcc
	s_cbranch_execz .LBB0_621
	v_or_b32_e32 v2, s10, v12
	v_ashrrev_i32_e32 v3, 31, v2
	v_lshlrev_b64 v[2:3], 12, v[2:3]
	v_lshl_add_u64 v[2:3], v[8:9], 0, v[2:3]
	v_mov_b64_e32 v[2:3], v[40:41]
	v_mov_b64_e32 v[4:5], v[42:43]
.LBB0_621:
	s_or_b64 exec, exec, s[26:27]
	v_mul_u32_u24_e32 v6, 0x84, v13
	v_add_u32_e32 v14, v6, v10
	v_add_u32_e32 v6, 0x420, v14
	s_waitcnt vmcnt(0)
	ds_write2_b32 v6, v2, v3 offset1:1
	v_add_u32_e32 v2, 0x428, v14
	ds_write2_b32 v2, v4, v5 offset1:1
	v_or_b32_e32 v11, 16, v13
	v_mov_b32_e32 v2, 0
	v_mov_b32_e32 v4, 0
	v_mov_b32_e32 v5, 0
	v_mov_b32_e32 v6, 0
	v_mov_b32_e32 v7, 0
	s_and_saveexec_b64 s[26:27], vcc
	s_cbranch_execz .LBB0_623
	v_or_b32_e32 v4, s10, v11
	v_ashrrev_i32_e32 v5, 31, v4
	v_lshlrev_b64 v[4:5], 12, v[4:5]
	v_lshl_add_u64 v[4:5], v[8:9], 0, v[4:5]
	v_mov_b64_e32 v[4:5], v[44:45]
	v_mov_b64_e32 v[6:7], v[46:47]
.LBB0_623:
	s_or_b64 exec, exec, s[26:27]
	v_add_u32_e32 v3, 0x840, v14
	s_waitcnt vmcnt(0)
	ds_write2_b32 v3, v4, v5 offset1:1
	v_add_u32_e32 v3, 0x848, v14
	ds_write2_b32 v3, v6, v7 offset1:1
	v_or_b32_e32 v10, 24, v13
	v_mov_b32_e32 v3, 0
	v_mov_b32_e32 v4, 0
	v_mov_b32_e32 v5, 0
	s_and_saveexec_b64 s[26:27], vcc
	s_cbranch_execz .LBB0_625
	v_or_b32_e32 v2, s10, v10
	v_ashrrev_i32_e32 v3, 31, v2
	v_lshlrev_b64 v[2:3], 12, v[2:3]
	v_lshl_add_u64 v[2:3], v[8:9], 0, v[2:3]
	v_mov_b64_e32 v[2:3], v[48:49]
	v_mov_b64_e32 v[4:5], v[50:51]
.LBB0_625:
	s_or_b64 exec, exec, s[26:27]
	v_add_u32_e32 v6, 0xc60, v14
	s_waitcnt vmcnt(0)
	ds_write2_b32 v6, v2, v3 offset1:1
	v_add_u32_e32 v2, 0xc68, v14
	ds_write2_b32 v2, v4, v5 offset1:1
	v_mov_b32_e32 v2, 0
	v_mov_b32_e32 v4, 0
	v_mov_b32_e32 v5, 0
	v_mov_b32_e32 v6, 0
	v_mov_b32_e32 v7, 0
	s_and_saveexec_b64 s[26:27], vcc
	s_cbranch_execz .LBB0_627
	v_or3_b32 v4, v13, s10, 32
	v_ashrrev_i32_e32 v5, 31, v4
	v_lshlrev_b64 v[4:5], 12, v[4:5]
	v_lshl_add_u64 v[4:5], v[8:9], 0, v[4:5]
	v_mov_b64_e32 v[4:5], v[52:53]
	v_mov_b64_e32 v[6:7], v[54:55]
.LBB0_627:
	s_or_b64 exec, exec, s[26:27]
	v_add_u32_e32 v3, 0x1080, v14
	s_waitcnt vmcnt(0)
	ds_write2_b32 v3, v4, v5 offset1:1
	v_add_u32_e32 v3, 0x1088, v14
	ds_write2_b32 v3, v6, v7 offset1:1
	v_mov_b32_e32 v3, 0
	v_mov_b32_e32 v4, 0
	v_mov_b32_e32 v5, 0
	s_and_saveexec_b64 s[26:27], vcc
	s_cbranch_execz .LBB0_629
	v_or3_b32 v2, v13, s10, 40
	v_ashrrev_i32_e32 v3, 31, v2
	v_lshlrev_b64 v[2:3], 12, v[2:3]
	v_lshl_add_u64 v[2:3], v[8:9], 0, v[2:3]
	v_mov_b64_e32 v[2:3], v[56:57]
	v_mov_b64_e32 v[4:5], v[58:59]
.LBB0_629:
	s_or_b64 exec, exec, s[26:27]
	v_add_u32_e32 v6, 0x14a0, v14
	s_waitcnt vmcnt(0)
	ds_write2_b32 v6, v2, v3 offset1:1
	v_add_u32_e32 v2, 0x14a8, v14
	ds_write2_b32 v2, v4, v5 offset1:1
	v_mov_b32_e32 v2, 0
	v_mov_b32_e32 v4, 0
	v_mov_b32_e32 v5, 0
	v_mov_b32_e32 v6, 0
	v_mov_b32_e32 v7, 0
	s_and_saveexec_b64 s[26:27], vcc
	s_cbranch_execz .LBB0_631
	v_or3_b32 v4, v13, s10, 48
	v_ashrrev_i32_e32 v5, 31, v4
	v_lshlrev_b64 v[4:5], 12, v[4:5]
	v_lshl_add_u64 v[4:5], v[8:9], 0, v[4:5]
	v_mov_b64_e32 v[4:5], v[60:61]
	v_mov_b64_e32 v[6:7], v[62:63]
.LBB0_631:
	s_or_b64 exec, exec, s[26:27]
	v_add_u32_e32 v3, 0x18c0, v14
	s_waitcnt vmcnt(0)
	ds_write2_b32 v3, v4, v5 offset1:1
	v_add_u32_e32 v3, 0x18c8, v14
	ds_write2_b32 v3, v6, v7 offset1:1
	v_mov_b32_e32 v3, 0
	v_mov_b32_e32 v4, 0
	v_mov_b32_e32 v5, 0
	s_and_saveexec_b64 s[26:27], vcc
	s_cbranch_execz .LBB0_633
	v_or3_b32 v2, v13, s10, 56
	v_ashrrev_i32_e32 v3, 31, v2
	v_lshlrev_b64 v[2:3], 12, v[2:3]
	v_lshl_add_u64 v[2:3], v[8:9], 0, v[2:3]
	v_mov_b64_e32 v[2:3], v[64:65]
	v_mov_b64_e32 v[4:5], v[66:67]

.LBB0_884:
	s_movk_i32 s6, 0x98
	v_readlane_b32 s10, v250, 57
	v_readlane_b32 s11, v250, 58
	s_load_dwordx2 s[6:7], s[10:11], s6 offset:0x0
	v_and_b32_e32 v3, 7, v8
	v_lshlrev_b32_e32 v2, 4, v3
	v_lshrrev_b32_e32 v9, 3, v10
	v_mul_u32_u24_e32 v11, 0x84, v9
	s_waitcnt lgkmcnt(0)
	s_add_u32 s10, s6, s17
	s_addc_u32 s11, s7, 0
	s_lshl_b32 s6, s27, 5
	s_add_i32 s7, s6, 0x1300
	s_and_b32 s6, s6, 32
	s_and_b32 s7, s7, 0x1fc0
	v_lshl_or_b32 v0, s6, 2, v2
	v_lshl_add_u64 v[12:13], s[10:11], 0, v[0:1]
	v_or_b32_e32 v0, s7, v9
	v_lshlrev_b32_e32 v0, 8, v0
	v_lshl_add_u64 v[4:5], v[12:13], 0, v[0:1]
	v_mov_b32_e32 v68, 0x800
	v_mov_b32_e32 v69, 0
	v_lshl_add_u64 v[70:71], v[4:5], 0, v[68:69]
	global_load_dwordx4 v[40:43], v[70:71], off
	v_lshl_add_u64 v[70:71], v[70:71], 0, v[68:69]
	global_load_dwordx4 v[44:47], v[70:71], off
	v_lshl_add_u64 v[70:71], v[70:71], 0, v[68:69]
	global_load_dwordx4 v[48:51], v[70:71], off
	v_lshl_add_u64 v[70:71], v[70:71], 0, v[68:69]
	global_load_dwordx4 v[52:55], v[70:71], off
	v_lshl_add_u64 v[70:71], v[70:71], 0, v[68:69]
	global_load_dwordx4 v[56:59], v[70:71], off
	v_lshl_add_u64 v[70:71], v[70:71], 0, v[68:69]
	global_load_dwordx4 v[60:63], v[70:71], off
	v_lshl_add_u64 v[70:71], v[70:71], 0, v[68:69]
	global_load_dwordx4 v[64:67], v[70:71], off
	global_load_dwordx4 v[4:7], v[4:5], off
	v_add3_u32 v11, s26, v2, v11
	v_or_b32_e32 v30, 8, v9
	v_add_u32_e32 v14, 0x420, v11
	v_or_b32_e32 v31, 16, v9
	v_or_b32_e32 v32, 24, v9
	v_readlane_b32 s10, v249, 46
	s_waitcnt vmcnt(0)
	ds_write2_b32 v11, v4, v5 offset1:1
	ds_write2_b32 v11, v6, v7 offset0:2 offset1:3
	v_or_b32_e32 v4, s7, v30
	v_lshlrev_b32_e32 v4, 8, v4
	v_mov_b32_e32 v5, v1
	v_lshl_add_u64 v[4:5], v[12:13], 0, v[4:5]
	v_mov_b64_e32 v[4:5], v[40:41]
	v_mov_b64_e32 v[6:7], v[42:43]
	s_waitcnt vmcnt(0)
	ds_write2_b32 v14, v4, v5 offset1:1
	v_add_u32_e32 v4, 0x428, v11
	ds_write2_b32 v4, v6, v7 offset1:1
	v_or_b32_e32 v4, s7, v31
	v_lshlrev_b32_e32 v4, 8, v4
	v_mov_b32_e32 v5, v1
	v_lshl_add_u64 v[4:5], v[12:13], 0, v[4:5]
	v_mov_b64_e32 v[4:5], v[44:45]
	v_mov_b64_e32 v[6:7], v[46:47]
	v_add_u32_e32 v14, 0x840, v11
	s_waitcnt vmcnt(0)
	ds_write2_b32 v14, v4, v5 offset1:1
	v_add_u32_e32 v4, 0x848, v11
	ds_write2_b32 v4, v6, v7 offset1:1
	v_or_b32_e32 v4, s7, v32
	v_lshlrev_b32_e32 v4, 8, v4
	v_mov_b32_e32 v5, v1
	v_lshl_add_u64 v[4:5], v[12:13], 0, v[4:5]
	v_mov_b64_e32 v[4:5], v[48:49]
	v_mov_b64_e32 v[6:7], v[50:51]
	v_add_u32_e32 v14, 0xc60, v11
	s_lshl_b32 s7, s7, 1
	s_add_u32 s10, s10, s7
	v_readlane_b32 s7, v249, 47
	s_addc_u32 s11, s7, 0
	s_waitcnt vmcnt(0)
	ds_write2_b32 v14, v4, v5 offset1:1
	v_add_u32_e32 v4, 0xc68, v11
	ds_write2_b32 v4, v6, v7 offset1:1
	v_or_b32_e32 v4, 0x2000, v0
	v_mov_b32_e32 v5, v1
	v_lshl_add_u64 v[4:5], v[12:13], 0, v[4:5]
	v_mov_b64_e32 v[4:5], v[52:53]
	v_mov_b64_e32 v[6:7], v[54:55]
	v_add_u32_e32 v14, 0x1080, v11
	s_waitcnt vmcnt(0)
	ds_write2_b32 v14, v4, v5 offset1:1
	v_add_u32_e32 v4, 0x1088, v11
	ds_write2_b32 v4, v6, v7 offset1:1
	v_or_b32_e32 v4, 0x2800, v0
	v_mov_b32_e32 v5, v1
	v_lshl_add_u64 v[4:5], v[12:13], 0, v[4:5]
	v_mov_b64_e32 v[4:5], v[56:57]
	v_mov_b64_e32 v[6:7], v[58:59]
	v_add_u32_e32 v14, 0x14a0, v11
	s_waitcnt vmcnt(0)
	ds_write2_b32 v14, v4, v5 offset1:1
	v_add_u32_e32 v4, 0x14a8, v11
	ds_write2_b32 v4, v6, v7 offset1:1
	v_or_b32_e32 v4, 0x3000, v0
	v_mov_b32_e32 v5, v1
	v_lshl_add_u64 v[4:5], v[12:13], 0, v[4:5]
	v_mov_b64_e32 v[4:5], v[60:61]
	v_mov_b64_e32 v[6:7], v[62:63]
	v_add_u32_e32 v14, 0x18c0, v11
	v_or_b32_e32 v0, 0x3800, v0
	s_waitcnt vmcnt(0)
	ds_write2_b32 v14, v4, v5 offset1:1
	v_add_u32_e32 v4, 0x18c8, v11
	ds_write2_b32 v4, v6, v7 offset1:1
	v_lshl_add_u64 v[4:5], v[12:13], 0, v[0:1]
	v_mov_b64_e32 v[4:5], v[64:65]
	v_mov_b64_e32 v[6:7], v[66:67]
	v_add_u32_e32 v0, 0x1ce0, v11
	s_waitcnt vmcnt(0)
	ds_write2_b32 v0, v4, v5 offset1:1
	v_add_u32_e32 v0, 0x1ce8, v11
	ds_write2_b32 v0, v6, v7 offset1:1
	v_mul_u32_u24_e32 v0, 0x420, v3
	v_lshlrev_b32_e32 v4, 2, v9
	s_waitcnt lgkmcnt(0)
	v_or_b32_e32 v11, s6, v9
	v_add3_u32 v9, s26, v0, v4
	ds_read2_b32 v[12:13], v9 offset0:198 offset1:206
	ds_read2_b32 v[14:15], v9 offset0:231 offset1:239
	ds_read2_b32 v[16:17], v9 offset0:132 offset1:140
	ds_read2_b32 v[18:19], v9 offset0:165 offset1:173
	ds_read2_b32 v[20:21], v9 offset0:66 offset1:74
	ds_read2_b32 v[22:23], v9 offset0:99 offset1:107
	ds_read2_b32 v[24:25], v9 offset0:33 offset1:41
	ds_read2_b32 v[26:27], v9 offset1:8
	v_mov_b32_e32 v3, v1
	v_lshl_add_u64 v[2:3], s[10:11], 0, v[2:3]
	v_lshlrev_b32_e32 v0, 9, v11
	v_lshl_add_u64 v[28:29], v[2:3], 0, v[0:1]
	v_or_b32_e32 v0, s6, v30
	s_waitcnt lgkmcnt(6)
	v_cvt_pk_bf16_f32 v7, v12, v14
	s_waitcnt lgkmcnt(4)
	v_cvt_pk_bf16_f32 v6, v16, v18
	s_waitcnt lgkmcnt(2)
	v_cvt_pk_bf16_f32 v5, v20, v22
	s_waitcnt lgkmcnt(0)
	v_cvt_pk_bf16_f32 v4, v26, v24
	v_lshlrev_b32_e32 v0, 9, v0
	global_store_dwordx4 v[28:29], v[4:7], off
	s_nop 1
	v_cvt_pk_bf16_f32 v7, v13, v15
	v_cvt_pk_bf16_f32 v6, v17, v19
	v_cvt_pk_bf16_f32 v5, v21, v23
	v_cvt_pk_bf16_f32 v4, v27, v25
	v_lshl_add_u64 v[12:13], v[2:3], 0, v[0:1]
	global_store_dwordx4 v[12:13], v[4:7], off
	ds_read2_b32 v[12:13], v9 offset0:214 offset1:222
	ds_read2_b32 v[14:15], v9 offset0:247 offset1:255
	ds_read2_b32 v[16:17], v9 offset0:148 offset1:156
	ds_read2_b32 v[18:19], v9 offset0:181 offset1:189
	ds_read2_b32 v[20:21], v9 offset0:82 offset1:90
	ds_read2_b32 v[22:23], v9 offset0:115 offset1:123
	ds_read2_b32 v[24:25], v9 offset0:49 offset1:57
	ds_read2_b32 v[26:27], v9 offset0:16 offset1:24
	v_or_b32_e32 v0, s6, v31
	v_lshlrev_b32_e32 v0, 9, v0
	v_lshl_add_u64 v[28:29], v[2:3], 0, v[0:1]
	v_or_b32_e32 v0, s6, v32
	s_waitcnt lgkmcnt(6)
	v_cvt_pk_bf16_f32 v7, v12, v14
	s_waitcnt lgkmcnt(4)
	v_cvt_pk_bf16_f32 v6, v16, v18
	s_waitcnt lgkmcnt(2)
	v_cvt_pk_bf16_f32 v5, v20, v22
	s_waitcnt lgkmcnt(0)
	v_cvt_pk_bf16_f32 v4, v26, v24
	v_lshlrev_b32_e32 v0, 9, v0
	global_store_dwordx4 v[28:29], v[4:7], off
	v_lshl_add_u64 v[2:3], v[2:3], 0, v[0:1]
	s_nop 0
	v_cvt_pk_bf16_f32 v7, v13, v15
	v_cvt_pk_bf16_f32 v6, v17, v19
	v_cvt_pk_bf16_f32 v5, v21, v23
	v_cvt_pk_bf16_f32 v4, v27, v25
	global_store_dwordx4 v[2:3], v[4:7], off
	s_waitcnt lgkmcnt(0)

.LBB0_886:
	s_andn2_b64 vcc, exec, s[6:7]
	s_cbranch_vccnz .LBB0_888
	s_movk_i32 s6, 0x88
	v_readlane_b32 s10, v250, 57
	v_readlane_b32 s11, v250, 58
	s_load_dwordx2 s[6:7], s[10:11], s6 offset:0x0
	v_and_b32_e32 v3, 7, v8
	v_lshlrev_b32_e32 v2, 4, v3
	v_lshrrev_b32_e32 v9, 3, v10
	v_mul_u32_u24_e32 v11, 0x84, v9
	s_waitcnt lgkmcnt(0)
	s_add_u32 s10, s6, s17
	s_addc_u32 s11, s7, 0
	s_lshl_b32 s6, s27, 5
	s_add_i32 s7, s6, 0x1400
	s_and_b32 s6, s6, 32
	s_and_b32 s7, s7, 0x1fc0
	v_lshl_or_b32 v0, s6, 2, v2
	v_lshl_add_u64 v[12:13], s[10:11], 0, v[0:1]
	v_or_b32_e32 v0, s7, v9
	v_lshlrev_b32_e32 v0, 8, v0
	v_lshl_add_u64 v[4:5], v[12:13], 0, v[0:1]
	v_mov_b32_e32 v68, 0x800
	v_mov_b32_e32 v69, 0
	v_lshl_add_u64 v[70:71], v[4:5], 0, v[68:69]
	global_load_dwordx4 v[40:43], v[70:71], off
	v_lshl_add_u64 v[70:71], v[70:71], 0, v[68:69]
	global_load_dwordx4 v[44:47], v[70:71], off
	v_lshl_add_u64 v[70:71], v[70:71], 0, v[68:69]
	global_load_dwordx4 v[48:51], v[70:71], off
	v_lshl_add_u64 v[70:71], v[70:71], 0, v[68:69]
	global_load_dwordx4 v[52:55], v[70:71], off
	v_lshl_add_u64 v[70:71], v[70:71], 0, v[68:69]
	global_load_dwordx4 v[56:59], v[70:71], off
	v_lshl_add_u64 v[70:71], v[70:71], 0, v[68:69]
	global_load_dwordx4 v[60:63], v[70:71], off
	v_lshl_add_u64 v[70:71], v[70:71], 0, v[68:69]
	global_load_dwordx4 v[64:67], v[70:71], off
	global_load_dwordx4 v[4:7], v[4:5], off
	v_add3_u32 v11, s26, v2, v11
	v_or_b32_e32 v30, 8, v9
	v_add_u32_e32 v14, 0x420, v11
	v_or_b32_e32 v31, 16, v9
	v_or_b32_e32 v32, 24, v9
	v_readlane_b32 s10, v249, 48
	s_waitcnt vmcnt(0)
	ds_write2_b32 v11, v4, v5 offset1:1
	ds_write2_b32 v11, v6, v7 offset0:2 offset1:3
	v_or_b32_e32 v4, s7, v30
	v_lshlrev_b32_e32 v4, 8, v4
	v_mov_b32_e32 v5, v1
	v_lshl_add_u64 v[4:5], v[12:13], 0, v[4:5]
	v_mov_b64_e32 v[4:5], v[40:41]
	v_mov_b64_e32 v[6:7], v[42:43]
	s_waitcnt vmcnt(0)
	ds_write2_b32 v14, v4, v5 offset1:1
	v_add_u32_e32 v4, 0x428, v11
	ds_write2_b32 v4, v6, v7 offset1:1
	v_or_b32_e32 v4, s7, v31
	v_lshlrev_b32_e32 v4, 8, v4
	v_mov_b32_e32 v5, v1
	v_lshl_add_u64 v[4:5], v[12:13], 0, v[4:5]
	v_mov_b64_e32 v[4:5], v[44:45]
	v_mov_b64_e32 v[6:7], v[46:47]
	v_add_u32_e32 v14, 0x840, v11
	s_waitcnt vmcnt(0)
	ds_write2_b32 v14, v4, v5 offset1:1
	v_add_u32_e32 v4, 0x848, v11
	ds_write2_b32 v4, v6, v7 offset1:1
	v_or_b32_e32 v4, s7, v32
	v_lshlrev_b32_e32 v4, 8, v4
	v_mov_b32_e32 v5, v1
	v_lshl_add_u64 v[4:5], v[12:13], 0, v[4:5]
	v_mov_b64_e32 v[4:5], v[48:49]
	v_mov_b64_e32 v[6:7], v[50:51]
	v_add_u32_e32 v14, 0xc60, v11
	s_lshl_b32 s7, s7, 1
	s_add_u32 s10, s10, s7
	v_readlane_b32 s7, v249, 49
	s_addc_u32 s11, s7, 0
	s_waitcnt vmcnt(0)
	ds_write2_b32 v14, v4, v5 offset1:1
	v_add_u32_e32 v4, 0xc68, v11
	ds_write2_b32 v4, v6, v7 offset1:1
	v_or_b32_e32 v4, 0x2000, v0
	v_mov_b32_e32 v5, v1
	v_lshl_add_u64 v[4:5], v[12:13], 0, v[4:5]
	v_mov_b64_e32 v[4:5], v[52:53]
	v_mov_b64_e32 v[6:7], v[54:55]
	v_add_u32_e32 v14, 0x1080, v11
	s_waitcnt vmcnt(0)
	ds_write2_b32 v14, v4, v5 offset1:1
	v_add_u32_e32 v4, 0x1088, v11
	ds_write2_b32 v4, v6, v7 offset1:1
	v_or_b32_e32 v4, 0x2800, v0
	v_mov_b32_e32 v5, v1
	v_lshl_add_u64 v[4:5], v[12:13], 0, v[4:5]
	v_mov_b64_e32 v[4:5], v[56:57]
	v_mov_b64_e32 v[6:7], v[58:59]
	v_add_u32_e32 v14, 0x14a0, v11
	s_waitcnt vmcnt(0)
	ds_write2_b32 v14, v4, v5 offset1:1
	v_add_u32_e32 v4, 0x14a8, v11
	ds_write2_b32 v4, v6, v7 offset1:1
	v_or_b32_e32 v4, 0x3000, v0
	v_mov_b32_e32 v5, v1
	v_lshl_add_u64 v[4:5], v[12:13], 0, v[4:5]
	v_mov_b64_e32 v[4:5], v[60:61]
	v_mov_b64_e32 v[6:7], v[62:63]
	v_add_u32_e32 v14, 0x18c0, v11
	v_or_b32_e32 v0, 0x3800, v0
	s_waitcnt vmcnt(0)
	ds_write2_b32 v14, v4, v5 offset1:1
	v_add_u32_e32 v4, 0x18c8, v11
	ds_write2_b32 v4, v6, v7 offset1:1
	v_lshl_add_u64 v[4:5], v[12:13], 0, v[0:1]
	v_mov_b64_e32 v[4:5], v[64:65]
	v_mov_b64_e32 v[6:7], v[66:67]
	v_add_u32_e32 v0, 0x1ce0, v11
	s_waitcnt vmcnt(0)
	ds_write2_b32 v0, v4, v5 offset1:1
	v_add_u32_e32 v0, 0x1ce8, v11
	ds_write2_b32 v0, v6, v7 offset1:1
	v_mul_u32_u24_e32 v0, 0x420, v3
	v_lshlrev_b32_e32 v4, 2, v9
	s_waitcnt lgkmcnt(0)
	v_or_b32_e32 v11, s6, v9
	v_add3_u32 v9, s26, v0, v4
	ds_read2_b32 v[12:13], v9 offset0:198 offset1:206
	ds_read2_b32 v[14:15], v9 offset0:231 offset1:239
	ds_read2_b32 v[16:17], v9 offset0:132 offset1:140
	ds_read2_b32 v[18:19], v9 offset0:165 offset1:173
	ds_read2_b32 v[20:21], v9 offset0:66 offset1:74
	ds_read2_b32 v[22:23], v9 offset0:99 offset1:107
	ds_read2_b32 v[24:25], v9 offset0:33 offset1:41
	ds_read2_b32 v[26:27], v9 offset1:8
	v_mov_b32_e32 v3, v1
	v_lshl_add_u64 v[2:3], s[10:11], 0, v[2:3]
	v_lshlrev_b32_e32 v0, 9, v11
	v_lshl_add_u64 v[28:29], v[2:3], 0, v[0:1]
	v_or_b32_e32 v0, s6, v30
	s_waitcnt lgkmcnt(6)
	v_cvt_pk_bf16_f32 v7, v12, v14
	s_waitcnt lgkmcnt(4)
	v_cvt_pk_bf16_f32 v6, v16, v18
	s_waitcnt lgkmcnt(2)
	v_cvt_pk_bf16_f32 v5, v20, v22
	s_waitcnt lgkmcnt(0)
	v_cvt_pk_bf16_f32 v4, v26, v24
	v_lshlrev_b32_e32 v0, 9, v0
	global_store_dwordx4 v[28:29], v[4:7], off
	s_nop 1
	v_cvt_pk_bf16_f32 v7, v13, v15
	v_cvt_pk_bf16_f32 v6, v17, v19
	v_cvt_pk_bf16_f32 v5, v21, v23
	v_cvt_pk_bf16_f32 v4, v27, v25
	v_lshl_add_u64 v[12:13], v[2:3], 0, v[0:1]
	global_store_dwordx4 v[12:13], v[4:7], off
	ds_read2_b32 v[12:13], v9 offset0:214 offset1:222
	ds_read2_b32 v[14:15], v9 offset0:247 offset1:255
	ds_read2_b32 v[16:17], v9 offset0:148 offset1:156
	ds_read2_b32 v[18:19], v9 offset0:181 offset1:189
	ds_read2_b32 v[20:21], v9 offset0:82 offset1:90
	ds_read2_b32 v[22:23], v9 offset0:115 offset1:123
	ds_read2_b32 v[24:25], v9 offset0:49 offset1:57
	ds_read2_b32 v[26:27], v9 offset0:16 offset1:24
	v_or_b32_e32 v0, s6, v31
	v_lshlrev_b32_e32 v0, 9, v0
	v_lshl_add_u64 v[28:29], v[2:3], 0, v[0:1]
	v_or_b32_e32 v0, s6, v32
	s_waitcnt lgkmcnt(6)
	v_cvt_pk_bf16_f32 v7, v12, v14
	s_waitcnt lgkmcnt(4)
	v_cvt_pk_bf16_f32 v6, v16, v18
	s_waitcnt lgkmcnt(2)
	v_cvt_pk_bf16_f32 v5, v20, v22
	s_waitcnt lgkmcnt(0)
	v_cvt_pk_bf16_f32 v4, v26, v24
	v_lshlrev_b32_e32 v0, 9, v0
	global_store_dwordx4 v[28:29], v[4:7], off
	v_lshl_add_u64 v[2:3], v[2:3], 0, v[0:1]
	s_nop 0
	v_cvt_pk_bf16_f32 v7, v13, v15
	v_cvt_pk_bf16_f32 v6, v17, v19
	v_cvt_pk_bf16_f32 v5, v21, v23
	v_cvt_pk_bf16_f32 v4, v27, v25
	global_store_dwordx4 v[2:3], v[4:7], off
	s_waitcnt lgkmcnt(0)

.LBB0_889:
	s_andn2_b64 vcc, exec, s[6:7]
	s_cbranch_vccnz .LBB0_891
	s_movk_i32 s6, 0x90
	v_readlane_b32 s10, v250, 57
	v_readlane_b32 s11, v250, 58
	s_load_dwordx2 s[6:7], s[10:11], s6 offset:0x0
	v_readlane_b32 s10, v249, 50
	v_and_b32_e32 v3, 7, v8
	v_lshlrev_b32_e32 v2, 4, v3
	v_lshrrev_b32_e32 v9, 3, v10
	s_waitcnt lgkmcnt(0)
	s_add_u32 s10, s6, s10
	s_addc_u32 s11, s7, 0
	s_lshl_b32 s6, s27, 3
	s_addk_i32 s6, 0x500
	s_and_b32 s7, s6, 0x7c0
	s_lshl_b32 s6, s27, 5
	s_and_b32 s6, s6, 0xe0
	v_lshl_or_b32 v0, s6, 2, v2
	v_lshl_add_u64 v[12:13], s[10:11], 0, v[0:1]
	v_or_b32_e32 v0, s7, v9
	v_lshlrev_b32_e32 v0, 10, v0
	v_lshl_add_u64 v[4:5], v[12:13], 0, v[0:1]
	v_mov_b32_e32 v68, 0x2000
	v_mov_b32_e32 v69, 0
	v_lshl_add_u64 v[70:71], v[4:5], 0, v[68:69]
	global_load_dwordx4 v[40:43], v[70:71], off
	v_lshl_add_u64 v[70:71], v[70:71], 0, v[68:69]
	global_load_dwordx4 v[44:47], v[70:71], off
	v_lshl_add_u64 v[70:71], v[70:71], 0, v[68:69]
	global_load_dwordx4 v[48:51], v[70:71], off
	v_lshl_add_u64 v[70:71], v[70:71], 0, v[68:69]
	global_load_dwordx4 v[52:55], v[70:71], off
	v_lshl_add_u64 v[70:71], v[70:71], 0, v[68:69]
	global_load_dwordx4 v[56:59], v[70:71], off
	v_lshl_add_u64 v[70:71], v[70:71], 0, v[68:69]
	global_load_dwordx4 v[60:63], v[70:71], off
	v_lshl_add_u64 v[70:71], v[70:71], 0, v[68:69]
	global_load_dwordx4 v[64:67], v[70:71], off
	global_load_dwordx4 v[4:7], v[4:5], off
	v_mul_u32_u24_e32 v11, 0x84, v9
	v_add3_u32 v11, s26, v2, v11
	v_or_b32_e32 v30, 8, v9
	v_add_u32_e32 v14, 0x420, v11
	v_or_b32_e32 v31, 16, v9
	v_or_b32_e32 v32, 24, v9
	v_readlane_b32 s10, v249, 51
	s_waitcnt vmcnt(0)
	ds_write2_b32 v11, v4, v5 offset1:1
	ds_write2_b32 v11, v6, v7 offset0:2 offset1:3
	v_or_b32_e32 v4, s7, v30
	v_lshlrev_b32_e32 v4, 10, v4
	v_mov_b32_e32 v5, v1
	v_lshl_add_u64 v[4:5], v[12:13], 0, v[4:5]
	v_mov_b64_e32 v[4:5], v[40:41]
	v_mov_b64_e32 v[6:7], v[42:43]
	s_waitcnt vmcnt(0)
	ds_write2_b32 v14, v4, v5 offset1:1
	v_add_u32_e32 v4, 0x428, v11
	ds_write2_b32 v4, v6, v7 offset1:1
	v_or_b32_e32 v4, s7, v31
	v_lshlrev_b32_e32 v4, 10, v4
	v_mov_b32_e32 v5, v1
	v_lshl_add_u64 v[4:5], v[12:13], 0, v[4:5]
	v_mov_b64_e32 v[4:5], v[44:45]
	v_mov_b64_e32 v[6:7], v[46:47]
	v_add_u32_e32 v14, 0x840, v11
	s_waitcnt vmcnt(0)
	ds_write2_b32 v14, v4, v5 offset1:1
	v_add_u32_e32 v4, 0x848, v11
	ds_write2_b32 v4, v6, v7 offset1:1
	v_or_b32_e32 v4, s7, v32
	v_lshlrev_b32_e32 v4, 10, v4
	v_mov_b32_e32 v5, v1
	v_lshl_add_u64 v[4:5], v[12:13], 0, v[4:5]
	v_mov_b64_e32 v[4:5], v[48:49]
	v_mov_b64_e32 v[6:7], v[50:51]
	v_add_u32_e32 v14, 0xc60, v11
	s_lshl_b32 s7, s7, 1
	s_add_u32 s10, s10, s7
	v_readlane_b32 s7, v249, 52
	s_addc_u32 s11, s7, 0
	s_waitcnt vmcnt(0)
	ds_write2_b32 v14, v4, v5 offset1:1
	v_add_u32_e32 v4, 0xc68, v11
	ds_write2_b32 v4, v6, v7 offset1:1
	v_or_b32_e32 v4, 0x8000, v0
	v_mov_b32_e32 v5, v1
	v_lshl_add_u64 v[4:5], v[12:13], 0, v[4:5]
	v_mov_b64_e32 v[4:5], v[52:53]
	v_mov_b64_e32 v[6:7], v[54:55]
	v_add_u32_e32 v14, 0x1080, v11
	s_waitcnt vmcnt(0)
	ds_write2_b32 v14, v4, v5 offset1:1
	v_add_u32_e32 v4, 0x1088, v11
	ds_write2_b32 v4, v6, v7 offset1:1
	v_or_b32_e32 v4, 0xa000, v0
	v_mov_b32_e32 v5, v1
	v_lshl_add_u64 v[4:5], v[12:13], 0, v[4:5]
	v_mov_b64_e32 v[4:5], v[56:57]
	v_mov_b64_e32 v[6:7], v[58:59]
	v_add_u32_e32 v14, 0x14a0, v11
	s_waitcnt vmcnt(0)
	ds_write2_b32 v14, v4, v5 offset1:1
	v_add_u32_e32 v4, 0x14a8, v11
	ds_write2_b32 v4, v6, v7 offset1:1
	v_or_b32_e32 v4, 0xc000, v0
	v_mov_b32_e32 v5, v1
	v_lshl_add_u64 v[4:5], v[12:13], 0, v[4:5]
	v_mov_b64_e32 v[4:5], v[60:61]
	v_mov_b64_e32 v[6:7], v[62:63]
	v_add_u32_e32 v14, 0x18c0, v11
	v_or_b32_e32 v0, 0xe000, v0
	s_waitcnt vmcnt(0)
	ds_write2_b32 v14, v4, v5 offset1:1
	v_add_u32_e32 v4, 0x18c8, v11
	ds_write2_b32 v4, v6, v7 offset1:1
	v_lshl_add_u64 v[4:5], v[12:13], 0, v[0:1]
	v_mov_b64_e32 v[4:5], v[64:65]
	v_mov_b64_e32 v[6:7], v[66:67]
	v_add_u32_e32 v0, 0x1ce0, v11
	s_waitcnt vmcnt(0)
	ds_write2_b32 v0, v4, v5 offset1:1
	v_add_u32_e32 v0, 0x1ce8, v11
	ds_write2_b32 v0, v6, v7 offset1:1
	v_mul_u32_u24_e32 v0, 0x420, v3
	v_lshlrev_b32_e32 v4, 2, v9
	s_waitcnt lgkmcnt(0)
	v_or_b32_e32 v11, s6, v9
	v_add3_u32 v9, s26, v0, v4
	ds_read2_b32 v[12:13], v9 offset0:198 offset1:206
	ds_read2_b32 v[14:15], v9 offset0:231 offset1:239
	ds_read2_b32 v[16:17], v9 offset0:132 offset1:140
	ds_read2_b32 v[18:19], v9 offset0:165 offset1:173
	ds_read2_b32 v[20:21], v9 offset0:66 offset1:74
	ds_read2_b32 v[22:23], v9 offset0:99 offset1:107
	ds_read2_b32 v[24:25], v9 offset0:33 offset1:41
	ds_read2_b32 v[26:27], v9 offset1:8
	v_mov_b32_e32 v3, v1
	v_lshl_add_u64 v[2:3], s[10:11], 0, v[2:3]
	v_lshlrev_b32_e32 v0, 12, v11
	v_lshl_add_u64 v[28:29], v[2:3], 0, v[0:1]
	v_or_b32_e32 v0, s6, v30
	s_waitcnt lgkmcnt(6)
	v_cvt_pk_bf16_f32 v7, v12, v14
	s_waitcnt lgkmcnt(4)
	v_cvt_pk_bf16_f32 v6, v16, v18
	s_waitcnt lgkmcnt(2)
	v_cvt_pk_bf16_f32 v5, v20, v22
	s_waitcnt lgkmcnt(0)
	v_cvt_pk_bf16_f32 v4, v26, v24
	v_lshlrev_b32_e32 v0, 12, v0
	global_store_dwordx4 v[28:29], v[4:7], off
	s_nop 1
	v_cvt_pk_bf16_f32 v7, v13, v15
	v_cvt_pk_bf16_f32 v6, v17, v19
	v_cvt_pk_bf16_f32 v5, v21, v23
	v_cvt_pk_bf16_f32 v4, v27, v25
	v_lshl_add_u64 v[12:13], v[2:3], 0, v[0:1]
	global_store_dwordx4 v[12:13], v[4:7], off
	ds_read2_b32 v[12:13], v9 offset0:214 offset1:222
	ds_read2_b32 v[14:15], v9 offset0:247 offset1:255
	ds_read2_b32 v[16:17], v9 offset0:148 offset1:156
	ds_read2_b32 v[18:19], v9 offset0:181 offset1:189
	ds_read2_b32 v[20:21], v9 offset0:82 offset1:90
	ds_read2_b32 v[22:23], v9 offset0:115 offset1:123
	ds_read2_b32 v[24:25], v9 offset0:49 offset1:57
	ds_read2_b32 v[26:27], v9 offset0:16 offset1:24
	v_or_b32_e32 v0, s6, v31
	v_lshlrev_b32_e32 v0, 12, v0
	v_lshl_add_u64 v[28:29], v[2:3], 0, v[0:1]
	v_or_b32_e32 v0, s6, v32
	s_waitcnt lgkmcnt(6)
	v_cvt_pk_bf16_f32 v7, v12, v14
	s_waitcnt lgkmcnt(4)
	v_cvt_pk_bf16_f32 v6, v16, v18
	s_waitcnt lgkmcnt(2)
	v_cvt_pk_bf16_f32 v5, v20, v22
	s_waitcnt lgkmcnt(0)
	v_cvt_pk_bf16_f32 v4, v26, v24
	v_lshlrev_b32_e32 v0, 12, v0
	global_store_dwordx4 v[28:29], v[4:7], off
	v_lshl_add_u64 v[2:3], v[2:3], 0, v[0:1]
	s_nop 0
	v_cvt_pk_bf16_f32 v7, v13, v15
	v_cvt_pk_bf16_f32 v6, v17, v19
	v_cvt_pk_bf16_f32 v5, v21, v23
	v_cvt_pk_bf16_f32 v4, v27, v25
	global_store_dwordx4 v[2:3], v[4:7], off
	s_waitcnt lgkmcnt(0)

.LBB0_892:
	s_andn2_b64 vcc, exec, s[6:7]
	s_cbranch_vccnz .LBB0_894
	s_movk_i32 s6, 0x80
	v_readlane_b32 s10, v250, 57
	v_readlane_b32 s11, v250, 58
	s_load_dwordx2 s[6:7], s[10:11], s6 offset:0x0
	v_readlane_b32 s10, v249, 50
	v_and_b32_e32 v3, 7, v8
	v_lshlrev_b32_e32 v2, 4, v3
	v_lshrrev_b32_e32 v9, 3, v10
	s_waitcnt lgkmcnt(0)
	s_add_u32 s10, s6, s10
	s_addc_u32 s11, s7, 0
	s_lshl_b32 s6, s27, 3
	s_addk_i32 s6, 0x500
	s_and_b32 s7, s6, 0x7c0
	s_lshl_b32 s6, s27, 5
	s_and_b32 s6, s6, 0xe0
	v_lshl_or_b32 v0, s6, 2, v2
	v_lshl_add_u64 v[12:13], s[10:11], 0, v[0:1]
	v_or_b32_e32 v0, s7, v9
	v_lshlrev_b32_e32 v0, 10, v0
	v_lshl_add_u64 v[4:5], v[12:13], 0, v[0:1]
	v_mov_b32_e32 v68, 0x2000
	v_mov_b32_e32 v69, 0
	v_lshl_add_u64 v[70:71], v[4:5], 0, v[68:69]
	global_load_dwordx4 v[40:43], v[70:71], off
	v_lshl_add_u64 v[70:71], v[70:71], 0, v[68:69]
	global_load_dwordx4 v[44:47], v[70:71], off
	v_lshl_add_u64 v[70:71], v[70:71], 0, v[68:69]
	global_load_dwordx4 v[48:51], v[70:71], off
	v_lshl_add_u64 v[70:71], v[70:71], 0, v[68:69]
	global_load_dwordx4 v[52:55], v[70:71], off
	v_lshl_add_u64 v[70:71], v[70:71], 0, v[68:69]
	global_load_dwordx4 v[56:59], v[70:71], off
	v_lshl_add_u64 v[70:71], v[70:71], 0, v[68:69]
	global_load_dwordx4 v[60:63], v[70:71], off
	v_lshl_add_u64 v[70:71], v[70:71], 0, v[68:69]
	global_load_dwordx4 v[64:67], v[70:71], off
	global_load_dwordx4 v[4:7], v[4:5], off
	v_mul_u32_u24_e32 v11, 0x84, v9
	v_add3_u32 v11, s26, v2, v11
	v_or_b32_e32 v30, 8, v9
	v_add_u32_e32 v14, 0x420, v11
	v_or_b32_e32 v31, 16, v9
	v_or_b32_e32 v32, 24, v9
	v_readlane_b32 s10, v249, 53
	s_waitcnt vmcnt(0)
	ds_write2_b32 v11, v4, v5 offset1:1
	ds_write2_b32 v11, v6, v7 offset0:2 offset1:3
	v_or_b32_e32 v4, s7, v30
	v_lshlrev_b32_e32 v4, 10, v4
	v_mov_b32_e32 v5, v1
	v_lshl_add_u64 v[4:5], v[12:13], 0, v[4:5]
	v_mov_b64_e32 v[4:5], v[40:41]
	v_mov_b64_e32 v[6:7], v[42:43]
	s_waitcnt vmcnt(0)
	ds_write2_b32 v14, v4, v5 offset1:1
	v_add_u32_e32 v4, 0x428, v11
	ds_write2_b32 v4, v6, v7 offset1:1
	v_or_b32_e32 v4, s7, v31
	v_lshlrev_b32_e32 v4, 10, v4
	v_mov_b32_e32 v5, v1
	v_lshl_add_u64 v[4:5], v[12:13], 0, v[4:5]
	v_mov_b64_e32 v[4:5], v[44:45]
	v_mov_b64_e32 v[6:7], v[46:47]
	v_add_u32_e32 v14, 0x840, v11
	s_waitcnt vmcnt(0)
	ds_write2_b32 v14, v4, v5 offset1:1
	v_add_u32_e32 v4, 0x848, v11
	ds_write2_b32 v4, v6, v7 offset1:1
	v_or_b32_e32 v4, s7, v32
	v_lshlrev_b32_e32 v4, 10, v4
	v_mov_b32_e32 v5, v1
	v_lshl_add_u64 v[4:5], v[12:13], 0, v[4:5]
	v_mov_b64_e32 v[4:5], v[48:49]
	v_mov_b64_e32 v[6:7], v[50:51]
	v_add_u32_e32 v14, 0xc60, v11
	s_lshl_b32 s7, s7, 1
	s_add_u32 s10, s10, s7
	v_readlane_b32 s7, v249, 54
	s_addc_u32 s11, s7, 0
	s_waitcnt vmcnt(0)
	ds_write2_b32 v14, v4, v5 offset1:1
	v_add_u32_e32 v4, 0xc68, v11
	ds_write2_b32 v4, v6, v7 offset1:1
	v_or_b32_e32 v4, 0x8000, v0
	v_mov_b32_e32 v5, v1
	v_lshl_add_u64 v[4:5], v[12:13], 0, v[4:5]
	v_mov_b64_e32 v[4:5], v[52:53]
	v_mov_b64_e32 v[6:7], v[54:55]
	v_add_u32_e32 v14, 0x1080, v11
	s_waitcnt vmcnt(0)
	ds_write2_b32 v14, v4, v5 offset1:1
	v_add_u32_e32 v4, 0x1088, v11
	ds_write2_b32 v4, v6, v7 offset1:1
	v_or_b32_e32 v4, 0xa000, v0
	v_mov_b32_e32 v5, v1
	v_lshl_add_u64 v[4:5], v[12:13], 0, v[4:5]
	v_mov_b64_e32 v[4:5], v[56:57]
	v_mov_b64_e32 v[6:7], v[58:59]
	v_add_u32_e32 v14, 0x14a0, v11
	s_waitcnt vmcnt(0)
	ds_write2_b32 v14, v4, v5 offset1:1
	v_add_u32_e32 v4, 0x14a8, v11
	ds_write2_b32 v4, v6, v7 offset1:1
	v_or_b32_e32 v4, 0xc000, v0
	v_mov_b32_e32 v5, v1
	v_lshl_add_u64 v[4:5], v[12:13], 0, v[4:5]
	v_mov_b64_e32 v[4:5], v[60:61]
	v_mov_b64_e32 v[6:7], v[62:63]
	v_add_u32_e32 v14, 0x18c0, v11
	v_or_b32_e32 v0, 0xe000, v0
	s_waitcnt vmcnt(0)
	ds_write2_b32 v14, v4, v5 offset1:1
	v_add_u32_e32 v4, 0x18c8, v11
	ds_write2_b32 v4, v6, v7 offset1:1
	v_lshl_add_u64 v[4:5], v[12:13], 0, v[0:1]
	v_mov_b64_e32 v[4:5], v[64:65]
	v_mov_b64_e32 v[6:7], v[66:67]
	v_add_u32_e32 v0, 0x1ce0, v11
	s_waitcnt vmcnt(0)
	ds_write2_b32 v0, v4, v5 offset1:1
	v_add_u32_e32 v0, 0x1ce8, v11
	ds_write2_b32 v0, v6, v7 offset1:1
	v_mul_u32_u24_e32 v0, 0x420, v3
	v_lshlrev_b32_e32 v4, 2, v9
	s_waitcnt lgkmcnt(0)
	v_or_b32_e32 v11, s6, v9
	v_add3_u32 v9, s26, v0, v4
	ds_read2_b32 v[12:13], v9 offset0:198 offset1:206
	ds_read2_b32 v[14:15], v9 offset0:231 offset1:239
	ds_read2_b32 v[16:17], v9 offset0:132 offset1:140
	ds_read2_b32 v[18:19], v9 offset0:165 offset1:173
	ds_read2_b32 v[20:21], v9 offset0:66 offset1:74
	ds_read2_b32 v[22:23], v9 offset0:99 offset1:107
	ds_read2_b32 v[24:25], v9 offset0:33 offset1:41
	ds_read2_b32 v[26:27], v9 offset1:8
	v_mov_b32_e32 v3, v1
	v_lshl_add_u64 v[2:3], s[10:11], 0, v[2:3]
	v_lshlrev_b32_e32 v0, 12, v11
	v_lshl_add_u64 v[28:29], v[2:3], 0, v[0:1]
	v_or_b32_e32 v0, s6, v30
	s_waitcnt lgkmcnt(6)
	v_cvt_pk_bf16_f32 v7, v12, v14
	s_waitcnt lgkmcnt(4)
	v_cvt_pk_bf16_f32 v6, v16, v18
	s_waitcnt lgkmcnt(2)
	v_cvt_pk_bf16_f32 v5, v20, v22
	s_waitcnt lgkmcnt(0)
	v_cvt_pk_bf16_f32 v4, v26, v24
	v_lshlrev_b32_e32 v0, 12, v0
	global_store_dwordx4 v[28:29], v[4:7], off
	s_nop 1
	v_cvt_pk_bf16_f32 v7, v13, v15
	v_cvt_pk_bf16_f32 v6, v17, v19
	v_cvt_pk_bf16_f32 v5, v21, v23
	v_cvt_pk_bf16_f32 v4, v27, v25
	v_lshl_add_u64 v[12:13], v[2:3], 0, v[0:1]
	global_store_dwordx4 v[12:13], v[4:7], off
	ds_read2_b32 v[12:13], v9 offset0:214 offset1:222
	ds_read2_b32 v[14:15], v9 offset0:247 offset1:255
	ds_read2_b32 v[16:17], v9 offset0:148 offset1:156
	ds_read2_b32 v[18:19], v9 offset0:181 offset1:189
	ds_read2_b32 v[20:21], v9 offset0:82 offset1:90
	ds_read2_b32 v[22:23], v9 offset0:115 offset1:123
	ds_read2_b32 v[24:25], v9 offset0:49 offset1:57
	ds_read2_b32 v[26:27], v9 offset0:16 offset1:24
	v_or_b32_e32 v0, s6, v31
	v_lshlrev_b32_e32 v0, 12, v0
	v_lshl_add_u64 v[28:29], v[2:3], 0, v[0:1]
	v_or_b32_e32 v0, s6, v32
	s_waitcnt lgkmcnt(6)
	v_cvt_pk_bf16_f32 v7, v12, v14
	s_waitcnt lgkmcnt(4)
	v_cvt_pk_bf16_f32 v6, v16, v18
	s_waitcnt lgkmcnt(2)
	v_cvt_pk_bf16_f32 v5, v20, v22
	s_waitcnt lgkmcnt(0)
	v_cvt_pk_bf16_f32 v4, v26, v24
	v_lshlrev_b32_e32 v0, 12, v0
	global_store_dwordx4 v[28:29], v[4:7], off
	v_lshl_add_u64 v[2:3], v[2:3], 0, v[0:1]
	s_nop 0
	v_cvt_pk_bf16_f32 v7, v13, v15
	v_cvt_pk_bf16_f32 v6, v17, v19
	v_cvt_pk_bf16_f32 v5, v21, v23
	v_cvt_pk_bf16_f32 v4, v27, v25
	global_store_dwordx4 v[2:3], v[4:7], off
	s_waitcnt lgkmcnt(0)

.LBB0_895:
	s_andn2_b64 vcc, exec, s[6:7]
	s_cbranch_vccnz .LBB0_897
	s_sub_i32 s6, s27, 48
	s_lshr_b32 s10, s6, 3
	s_movk_i32 s6, 0x58
	v_readlane_b32 s12, v250, 57
	v_readlane_b32 s13, v250, 58
	s_load_dwordx2 s[6:7], s[12:13], s6 offset:0x0
	s_bfe_u32 s14, s36, 0x30006
	v_readlane_b32 s11, v249, 55
	v_and_b32_e32 v9, 7, v8
	v_lshrrev_b32_e32 v11, 3, v10
	s_waitcnt lgkmcnt(0)
	s_add_u32 s11, s6, s11
	s_addc_u32 s13, s7, 0
	s_lshl_b32 s68, s10, 14
	s_lshl_b64 s[6:7], s[68:69], 2
	s_add_u32 s12, s11, s6
	s_addc_u32 s13, s13, s7
	s_lshl_b32 s6, s10, 16
	s_add_u32 s7, s66, s6
	s_addc_u32 s10, s67, 0
	s_lshl_b32 s6, s27, 4
	s_and_b32 s11, s6, 64
	s_lshl_b32 s6, s14, 5
	s_add_i32 s16, s6, 0xffffff80
	s_cmp_lt_u32 s14, 4
	s_cselect_b32 s6, s6, s16
	v_lshl_or_b32 v0, v9, 2, s6
	v_lshl_add_u64 v[12:13], v[0:1], 2, s[12:13]
	v_or_b32_e32 v0, s11, v11
	v_lshlrev_b32_e32 v0, 9, v0
	v_lshl_add_u64 v[2:3], v[12:13], 0, v[0:1]
	v_mov_b32_e32 v68, 0x1000
	v_mov_b32_e32 v69, 0
	v_lshl_add_u64 v[70:71], v[2:3], 0, v[68:69]
	global_load_dwordx4 v[40:43], v[70:71], off
	v_lshl_add_u64 v[70:71], v[70:71], 0, v[68:69]
	global_load_dwordx4 v[44:47], v[70:71], off
	v_lshl_add_u64 v[70:71], v[70:71], 0, v[68:69]
	global_load_dwordx4 v[48:51], v[70:71], off
	v_lshl_add_u64 v[70:71], v[70:71], 0, v[68:69]
	global_load_dwordx4 v[52:55], v[70:71], off
	v_lshl_add_u64 v[70:71], v[70:71], 0, v[68:69]
	global_load_dwordx4 v[56:59], v[70:71], off
	v_lshl_add_u64 v[70:71], v[70:71], 0, v[68:69]
	global_load_dwordx4 v[60:63], v[70:71], off
	v_lshl_add_u64 v[70:71], v[70:71], 0, v[68:69]
	global_load_dwordx4 v[64:67], v[70:71], off
	global_load_dwordx4 v[4:7], v[2:3], off
	v_mul_u32_u24_e32 v3, 0x84, v11
	v_lshlrev_b32_e32 v2, 4, v9
	v_add3_u32 v3, s26, v2, v3
	v_or_b32_e32 v30, 8, v11
	v_add_u32_e32 v14, 0x420, v3
	v_or_b32_e32 v31, 16, v11
	v_or_b32_e32 v32, 24, v11
	s_waitcnt vmcnt(0)
	ds_write2_b32 v3, v4, v5 offset1:1
	ds_write2_b32 v3, v6, v7 offset0:2 offset1:3
	v_or_b32_e32 v4, s11, v30
	v_lshlrev_b32_e32 v4, 9, v4
	v_mov_b32_e32 v5, v1
	v_lshl_add_u64 v[4:5], v[12:13], 0, v[4:5]
	v_mov_b64_e32 v[4:5], v[40:41]
	v_mov_b64_e32 v[6:7], v[42:43]
	s_waitcnt vmcnt(0)
	ds_write2_b32 v14, v4, v5 offset1:1
	v_add_u32_e32 v4, 0x428, v3
	ds_write2_b32 v4, v6, v7 offset1:1
	v_or_b32_e32 v4, s11, v31
	v_lshlrev_b32_e32 v4, 9, v4
	v_mov_b32_e32 v5, v1
	v_lshl_add_u64 v[4:5], v[12:13], 0, v[4:5]
	v_mov_b64_e32 v[4:5], v[44:45]
	v_mov_b64_e32 v[6:7], v[46:47]
	v_add_u32_e32 v14, 0x840, v3
	s_waitcnt vmcnt(0)
	ds_write2_b32 v14, v4, v5 offset1:1
	v_add_u32_e32 v4, 0x848, v3
	ds_write2_b32 v4, v6, v7 offset1:1
	v_or_b32_e32 v4, s11, v32
	v_lshlrev_b32_e32 v4, 9, v4
	v_mov_b32_e32 v5, v1
	v_lshl_add_u64 v[4:5], v[12:13], 0, v[4:5]
	v_mov_b64_e32 v[4:5], v[48:49]
	v_mov_b64_e32 v[6:7], v[50:51]
	v_add_u32_e32 v14, 0xc60, v3
	s_lshl_b32 s11, s11, 1
	s_add_u32 s28, s7, s11
	s_addc_u32 s29, s10, 0
	s_mov_b64 s[10:11], 0x2610400
	s_waitcnt vmcnt(0)
	ds_write2_b32 v14, v4, v5 offset1:1
	v_add_u32_e32 v4, 0xc68, v3
	ds_write2_b32 v4, v6, v7 offset1:1
	v_or_b32_e32 v4, 0x4000, v0
	v_mov_b32_e32 v5, v1
	v_lshl_add_u64 v[4:5], v[12:13], 0, v[4:5]
	v_mov_b64_e32 v[4:5], v[52:53]
	v_mov_b64_e32 v[6:7], v[54:55]
	v_add_u32_e32 v14, 0x1080, v3
	s_waitcnt vmcnt(0)
	ds_write2_b32 v14, v4, v5 offset1:1
	v_add_u32_e32 v4, 0x1088, v3
	ds_write2_b32 v4, v6, v7 offset1:1
	v_or_b32_e32 v4, 0x5000, v0
	v_mov_b32_e32 v5, v1
	v_lshl_add_u64 v[4:5], v[12:13], 0, v[4:5]
	v_mov_b64_e32 v[4:5], v[56:57]
	v_mov_b64_e32 v[6:7], v[58:59]
	v_add_u32_e32 v14, 0x14a0, v3
	s_waitcnt vmcnt(0)
	ds_write2_b32 v14, v4, v5 offset1:1
	v_add_u32_e32 v4, 0x14a8, v3
	ds_write2_b32 v4, v6, v7 offset1:1
	v_or_b32_e32 v4, 0x6000, v0
	v_mov_b32_e32 v5, v1
	v_lshl_add_u64 v[4:5], v[12:13], 0, v[4:5]
	v_mov_b64_e32 v[4:5], v[60:61]
	v_mov_b64_e32 v[6:7], v[62:63]
	v_add_u32_e32 v14, 0x18c0, v3
	v_or_b32_e32 v0, 0x7000, v0
	s_waitcnt vmcnt(0)
	ds_write2_b32 v14, v4, v5 offset1:1
	v_add_u32_e32 v4, 0x18c8, v3
	ds_write2_b32 v4, v6, v7 offset1:1
	v_lshl_add_u64 v[4:5], v[12:13], 0, v[0:1]
	v_mov_b64_e32 v[4:5], v[64:65]
	v_mov_b64_e32 v[6:7], v[66:67]
	v_add_u32_e32 v0, 0x1ce0, v3
	s_waitcnt vmcnt(0)
	ds_write2_b32 v0, v4, v5 offset1:1
	v_add_u32_e32 v0, 0x1ce8, v3
	v_mov_b32_e32 v3, v1
	v_lshl_add_u64 v[2:3], s[28:29], 0, v[2:3]
	ds_write2_b32 v0, v6, v7 offset1:1
	v_mul_u32_u24_e32 v4, 0x420, v9
	v_lshl_add_u64 v[6:7], v[2:3], 0, s[10:11]
	v_lshlrev_b32_e32 v2, 2, v11
	s_waitcnt lgkmcnt(0)
	v_add3_u32 v9, s26, v4, v2
	ds_read2_b32 v[12:13], v9 offset0:198 offset1:206
	ds_read2_b32 v[14:15], v9 offset0:231 offset1:239
	ds_read2_b32 v[16:17], v9 offset0:132 offset1:140
	ds_read2_b32 v[18:19], v9 offset0:165 offset1:173
	ds_read2_b32 v[20:21], v9 offset0:66 offset1:74
	ds_read2_b32 v[22:23], v9 offset0:99 offset1:107
	ds_read2_b32 v[24:25], v9 offset0:33 offset1:41
	ds_read2_b32 v[26:27], v9 offset1:8
	v_or_b32_e32 v0, s6, v11
	v_lshlrev_b64 v[28:29], 8, v[0:1]
	s_waitcnt lgkmcnt(6)
	v_cvt_pk_bf16_f32 v5, v12, v14
	s_waitcnt lgkmcnt(4)
	v_cvt_pk_bf16_f32 v4, v16, v18
	s_waitcnt lgkmcnt(2)
	v_cvt_pk_bf16_f32 v3, v20, v22
	s_waitcnt lgkmcnt(0)
	v_cvt_pk_bf16_f32 v2, v26, v24
	v_lshl_add_u64 v[28:29], v[6:7], 0, v[28:29]
	v_or_b32_e32 v0, s6, v30
	global_store_dwordx4 v[28:29], v[2:5], off
	s_nop 1
	v_cvt_pk_bf16_f32 v5, v13, v15
	v_lshlrev_b64 v[12:13], 8, v[0:1]
	v_cvt_pk_bf16_f32 v4, v17, v19
	v_cvt_pk_bf16_f32 v3, v21, v23
	v_cvt_pk_bf16_f32 v2, v27, v25
	v_lshl_add_u64 v[12:13], v[6:7], 0, v[12:13]
	global_store_dwordx4 v[12:13], v[2:5], off
	ds_read2_b32 v[12:13], v9 offset0:214 offset1:222
	ds_read2_b32 v[14:15], v9 offset0:247 offset1:255
	ds_read2_b32 v[16:17], v9 offset0:148 offset1:156
	ds_read2_b32 v[18:19], v9 offset0:181 offset1:189
	ds_read2_b32 v[20:21], v9 offset0:82 offset1:90
	ds_read2_b32 v[22:23], v9 offset0:115 offset1:123
	ds_read2_b32 v[24:25], v9 offset0:49 offset1:57
	ds_read2_b32 v[26:27], v9 offset0:16 offset1:24
	v_or_b32_e32 v0, s6, v31
	v_lshlrev_b64 v[28:29], 8, v[0:1]
	s_waitcnt lgkmcnt(6)
	v_cvt_pk_bf16_f32 v5, v12, v14
	s_waitcnt lgkmcnt(4)
	v_cvt_pk_bf16_f32 v4, v16, v18
	s_waitcnt lgkmcnt(2)
	v_cvt_pk_bf16_f32 v3, v20, v22
	s_waitcnt lgkmcnt(0)
	v_cvt_pk_bf16_f32 v2, v26, v24
	v_lshl_add_u64 v[28:29], v[6:7], 0, v[28:29]
	v_or_b32_e32 v0, s6, v32
	global_store_dwordx4 v[28:29], v[2:5], off
	s_nop 1
	v_cvt_pk_bf16_f32 v5, v13, v15
	v_lshlrev_b64 v[12:13], 8, v[0:1]
	v_cvt_pk_bf16_f32 v4, v17, v19
	v_cvt_pk_bf16_f32 v3, v21, v23
	v_cvt_pk_bf16_f32 v2, v27, v25
	v_lshl_add_u64 v[6:7], v[6:7], 0, v[12:13]
	global_store_dwordx4 v[6:7], v[2:5], off
	s_waitcnt lgkmcnt(0)

.LBB0_898:
	s_andn2_b64 vcc, exec, s[6:7]
	s_cbranch_vccnz .LBB0_924
	s_ashr_i32 s6, s27, 31
	s_lshr_b32 s10, s6, 29
	s_movk_i32 s6, 0x48
	v_readlane_b32 s12, v250, 57
	v_readlane_b32 s13, v250, 58
	s_load_dwordx2 s[6:7], s[12:13], s6 offset:0x0
	s_add_i32 s10, s27, s10
	s_ashr_i32 s11, s10, 3
	s_and_b32 s10, s10, 0xfff8
	s_sub_i32 s10, s27, s10
	v_readlane_b32 s12, v249, 55
	s_waitcnt lgkmcnt(0)
	s_add_u32 s12, s6, s12
	s_addc_u32 s13, s7, 0
	s_lshl_b32 s6, s11, 14
	s_ashr_i32 s7, s6, 31
	s_lshl_b64 s[6:7], s[6:7], 2
	s_add_u32 s6, s12, s6
	s_addc_u32 s7, s13, s7
	s_bfe_i32 s12, s10, 0x80000
	s_bfe_u32 s12, s12, 0x2000d
	s_add_i32 s12, s10, s12
	s_bfe_i32 s13, s12, 0x80000
	s_and_b32 s12, s12, 0xfc
	s_sub_i32 s10, s10, s12
	s_sext_i32_i8 s10, s10
	v_and_b32_e32 v0, 7, v8
	s_sext_i32_i16 s13, s13
	s_lshl_b32 s10, s10, 5
	v_lshlrev_b32_e32 v3, 2, v0
	s_lshl_b32 s12, s13, 4
	v_or_b32_e32 v2, s10, v3
	s_and_b32 s28, s12, 0xffffffc0
	v_or_b32_e32 v4, 3, v2
	s_movk_i32 s12, 0x80
	v_cmp_gt_i32_e32 vcc, s12, v4
	v_lshrrev_b32_e32 v13, 3, v10
	v_mov_b32_e32 v6, 0
	v_cndmask_b32_e32 v4, 0, v2, vcc
	v_ashrrev_i32_e32 v5, 31, v4
	v_lshl_add_u64 v[8:9], v[4:5], 2, s[6:7]
	v_mov_b32_e32 v2, 0
	v_mov_b32_e32 v4, 0
	v_mov_b32_e32 v5, 0
	v_mov_b32_e32 v7, 0
	s_and_saveexec_b64 s[30:31], vcc
	s_cbranch_execz .LBB0_901
	v_or_b32_e32 v4, s28, v13
	v_ashrrev_i32_e32 v5, 31, v4
	v_lshlrev_b64 v[4:5], 9, v[4:5]
	v_lshl_add_u64 v[4:5], v[8:9], 0, v[4:5]
	v_mov_b32_e32 v68, 0x1000
	v_mov_b32_e32 v69, 0
	v_lshl_add_u64 v[70:71], v[4:5], 0, v[68:69]
	global_load_dwordx4 v[40:43], v[70:71], off
	v_lshl_add_u64 v[70:71], v[70:71], 0, v[68:69]
	global_load_dwordx4 v[44:47], v[70:71], off
	v_lshl_add_u64 v[70:71], v[70:71], 0, v[68:69]
	global_load_dwordx4 v[48:51], v[70:71], off
	v_lshl_add_u64 v[70:71], v[70:71], 0, v[68:69]
	global_load_dwordx4 v[52:55], v[70:71], off
	v_lshl_add_u64 v[70:71], v[70:71], 0, v[68:69]
	global_load_dwordx4 v[56:59], v[70:71], off
	v_lshl_add_u64 v[70:71], v[70:71], 0, v[68:69]
	global_load_dwordx4 v[60:63], v[70:71], off
	v_lshl_add_u64 v[70:71], v[70:71], 0, v[68:69]
	global_load_dwordx4 v[64:67], v[70:71], off
	global_load_dwordx4 v[4:7], v[4:5], off
.LBB0_901:
	s_or_b64 exec, exec, s[30:31]
	v_lshl_add_u32 v10, v3, 2, s26
	s_movk_i32 s6, 0x84
	v_mad_u32_u24 v3, v13, s6, v10
	s_waitcnt vmcnt(0)
	ds_write2_b32 v3, v4, v5 offset1:1
	ds_write2_b32 v3, v6, v7 offset0:2 offset1:3
	v_or_b32_e32 v12, 8, v13
	v_mov_b32_e32 v3, 0
	v_mov_b32_e32 v4, 0
	v_mov_b32_e32 v5, 0
	s_and_saveexec_b64 s[6:7], vcc
	s_cbranch_execz .LBB0_903
	v_or_b32_e32 v2, s28, v12
	v_ashrrev_i32_e32 v3, 31, v2
	v_lshlrev_b64 v[2:3], 9, v[2:3]
	v_lshl_add_u64 v[2:3], v[8:9], 0, v[2:3]
	v_mov_b64_e32 v[2:3], v[40:41]
	v_mov_b64_e32 v[4:5], v[42:43]
.LBB0_903:
	s_or_b64 exec, exec, s[6:7]
	v_mul_u32_u24_e32 v6, 0x84, v13
	v_add_u32_e32 v14, v6, v10
	v_add_u32_e32 v6, 0x420, v14
	s_waitcnt vmcnt(0)
	ds_write2_b32 v6, v2, v3 offset1:1
	v_add_u32_e32 v2, 0x428, v14
	ds_write2_b32 v2, v4, v5 offset1:1
	v_or_b32_e32 v11, 16, v13
	v_mov_b32_e32 v2, 0
	v_mov_b32_e32 v4, 0
	v_mov_b32_e32 v5, 0
	v_mov_b32_e32 v6, 0
	v_mov_b32_e32 v7, 0
	s_and_saveexec_b64 s[6:7], vcc
	s_cbranch_execz .LBB0_905
	v_or_b32_e32 v4, s28, v11
	v_ashrrev_i32_e32 v5, 31, v4
	v_lshlrev_b64 v[4:5], 9, v[4:5]
	v_lshl_add_u64 v[4:5], v[8:9], 0, v[4:5]
	v_mov_b64_e32 v[4:5], v[44:45]
	v_mov_b64_e32 v[6:7], v[46:47]
.LBB0_905:
	s_or_b64 exec, exec, s[6:7]
	v_add_u32_e32 v3, 0x840, v14
	s_waitcnt vmcnt(0)
	ds_write2_b32 v3, v4, v5 offset1:1
	v_add_u32_e32 v3, 0x848, v14
	ds_write2_b32 v3, v6, v7 offset1:1
	v_or_b32_e32 v10, 24, v13
	v_mov_b32_e32 v3, 0
	v_mov_b32_e32 v4, 0
	v_mov_b32_e32 v5, 0
	s_and_saveexec_b64 s[6:7], vcc
	s_cbranch_execz .LBB0_907
	v_or_b32_e32 v2, s28, v10
	v_ashrrev_i32_e32 v3, 31, v2
	v_lshlrev_b64 v[2:3], 9, v[2:3]
	v_lshl_add_u64 v[2:3], v[8:9], 0, v[2:3]
	v_mov_b64_e32 v[2:3], v[48:49]
	v_mov_b64_e32 v[4:5], v[50:51]
.LBB0_907:
	s_or_b64 exec, exec, s[6:7]
	v_add_u32_e32 v6, 0xc60, v14
	s_waitcnt vmcnt(0)
	ds_write2_b32 v6, v2, v3 offset1:1
	v_add_u32_e32 v2, 0xc68, v14
	ds_write2_b32 v2, v4, v5 offset1:1
	v_mov_b32_e32 v2, 0
	v_mov_b32_e32 v4, 0
	v_mov_b32_e32 v5, 0
	v_mov_b32_e32 v6, 0
	v_mov_b32_e32 v7, 0
	s_and_saveexec_b64 s[6:7], vcc
	s_cbranch_execz .LBB0_909
	v_or3_b32 v4, v13, s28, 32
	v_ashrrev_i32_e32 v5, 31, v4
	v_lshlrev_b64 v[4:5], 9, v[4:5]
	v_lshl_add_u64 v[4:5], v[8:9], 0, v[4:5]
	v_mov_b64_e32 v[4:5], v[52:53]
	v_mov_b64_e32 v[6:7], v[54:55]
.LBB0_909:
	s_or_b64 exec, exec, s[6:7]
	v_add_u32_e32 v3, 0x1080, v14
	s_waitcnt vmcnt(0)
	ds_write2_b32 v3, v4, v5 offset1:1
	v_add_u32_e32 v3, 0x1088, v14
	ds_write2_b32 v3, v6, v7 offset1:1
	v_mov_b32_e32 v3, 0
	v_mov_b32_e32 v4, 0
	v_mov_b32_e32 v5, 0
	s_and_saveexec_b64 s[6:7], vcc
	s_cbranch_execz .LBB0_911
	v_or3_b32 v2, v13, s28, 40
	v_ashrrev_i32_e32 v3, 31, v2
	v_lshlrev_b64 v[2:3], 9, v[2:3]
	v_lshl_add_u64 v[2:3], v[8:9], 0, v[2:3]
	v_mov_b64_e32 v[2:3], v[56:57]
	v_mov_b64_e32 v[4:5], v[58:59]
.LBB0_911:
	s_or_b64 exec, exec, s[6:7]
	v_add_u32_e32 v6, 0x14a0, v14
	s_waitcnt vmcnt(0)
	ds_write2_b32 v6, v2, v3 offset1:1
	v_add_u32_e32 v2, 0x14a8, v14
	ds_write2_b32 v2, v4, v5 offset1:1
	v_mov_b32_e32 v2, 0
	v_mov_b32_e32 v4, 0
	v_mov_b32_e32 v5, 0
	v_mov_b32_e32 v6, 0
	v_mov_b32_e32 v7, 0
	s_and_saveexec_b64 s[6:7], vcc
	s_cbranch_execz .LBB0_913
	v_or3_b32 v4, v13, s28, 48
	v_ashrrev_i32_e32 v5, 31, v4
	v_lshlrev_b64 v[4:5], 9, v[4:5]
	v_lshl_add_u64 v[4:5], v[8:9], 0, v[4:5]
	v_mov_b64_e32 v[4:5], v[60:61]
	v_mov_b64_e32 v[6:7], v[62:63]
.LBB0_913:
	s_or_b64 exec, exec, s[6:7]
	v_add_u32_e32 v3, 0x18c0, v14
	s_waitcnt vmcnt(0)
	ds_write2_b32 v3, v4, v5 offset1:1
	v_add_u32_e32 v3, 0x18c8, v14
	ds_write2_b32 v3, v6, v7 offset1:1
	v_mov_b32_e32 v3, 0
	v_mov_b32_e32 v4, 0
	v_mov_b32_e32 v5, 0
	s_and_saveexec_b64 s[6:7], vcc
	s_cbranch_execz .LBB0_915
	v_or3_b32 v2, v13, s28, 56
	v_ashrrev_i32_e32 v3, 31, v2
	v_lshlrev_b64 v[2:3], 9, v[2:3]
	v_lshl_add_u64 v[2:3], v[8:9], 0, v[2:3]
	v_mov_b64_e32 v[2:3], v[64:65]
	v_mov_b64_e32 v[4:5], v[66:67]

.LBB0_925:
	s_andn2_b64 vcc, exec, s[6:7]
	s_cbranch_vccnz .LBB0_1051
	v_mov_b32_e32 v13, v203
	s_nop 0
	v_readfirstlane_b32 s6, v13
	s_ashr_i32 s6, s6, 6
	s_add_i32 s26, s25, s6
	s_addk_i32 s26, 0xb500
	s_cmpk_gt_i32 s26, 0x21df
	s_cbranch_scc1 .LBB0_1051
	s_mulk_i32 s6, 0x2100
	s_add_i32 s25, s6, 0
	v_and_b32_e32 v12, 63, v13
	s_cmpk_gt_i32 s26, 0x57f
	s_mov_b64 s[6:7], -1
	s_cbranch_scc0 .LBB0_1032
	s_cmpk_gt_u32 s26, 0xaff
	s_cbranch_scc0 .LBB0_1013
	s_cmpk_gt_u32 s26, 0x107f
	s_cbranch_scc0 .LBB0_1011
	s_mov_b32 s6, 48
	v_readlane_b32 s10, v250, 57
	v_readlane_b32 s11, v250, 58
	s_load_dwordx2 s[6:7], s[10:11], s6 offset:0x0
	v_readlane_b32 s11, v249, 8
	s_mul_i32 s10, s11, 0x22a4000
	v_and_b32_e32 v8, 7, v13
	v_lshlrev_b32_e32 v10, 2, v8
	s_waitcnt lgkmcnt(0)
	s_add_u32 s6, s6, s10
	s_mul_hi_u32 s10, s11, 0x22a4000
	s_addc_u32 s7, s7, s10
	s_add_i32 s10, s26, 0xef80
	s_and_b32 s11, s10, 0xffff
	s_mulk_i32 s11, 0x75df
	s_lshr_b32 s11, s11, 23
	s_mul_i32 s14, s11, 0x116
	s_sub_i32 s10, s10, s14
	s_lshl_b32 s12, s11, 6
	s_lshl_b32 s11, s10, 5
	s_and_b32 s11, s11, 0xffe0
	v_or_b32_e32 v0, s11, v10
	s_movk_i32 s14, 0x22a4
	v_cmp_gt_u32_e64 s[28:29], s14, v0
	v_mov_b32_e32 v2, v1
	v_mov_b32_e32 v3, v1
	v_cndmask_b32_e64 v0, 0, v0, s[28:29]
	v_lshlrev_b32_e32 v0, 2, v0
	v_lshl_add_u64 v[6:7], s[6:7], 0, v[0:1]
	v_lshrrev_b32_e32 v9, 3, v12
	v_mov_b32_e32 v0, v1
	v_mov_b64_e32 v[4:5], v[2:3]
	s_mov_b32 s13, 40
	v_or_b32_e32 v11, s12, v9
	v_mov_b64_e32 v[2:3], v[0:1]
	s_and_saveexec_b64 s[6:7], s[28:29]
	s_cbranch_execz .LBB0_932
	v_mul_u32_u24_e32 v0, 0x22a4, v11
	v_lshlrev_b32_e32 v0, 2, v0
	v_lshl_add_u64 v[2:3], v[6:7], 0, v[0:1]
	v_mov_b32_e32 v68, 0x45480
	v_mov_b32_e32 v69, 0
	v_lshl_add_u64 v[70:71], v[2:3], 0, v[68:69]
	global_load_dwordx4 v[40:43], v[70:71], off
	v_lshl_add_u64 v[70:71], v[70:71], 0, v[68:69]
	global_load_dwordx4 v[44:47], v[70:71], off
	v_lshl_add_u64 v[70:71], v[70:71], 0, v[68:69]
	global_load_dwordx4 v[48:51], v[70:71], off
	v_lshl_add_u64 v[70:71], v[70:71], 0, v[68:69]
	global_load_dwordx4 v[52:55], v[70:71], off
	v_lshl_add_u64 v[70:71], v[70:71], 0, v[68:69]
	global_load_dwordx4 v[56:59], v[70:71], off
	v_lshl_add_u64 v[70:71], v[70:71], 0, v[68:69]
	global_load_dwordx4 v[60:63], v[70:71], off
	v_lshl_add_u64 v[70:71], v[70:71], 0, v[68:69]
	global_load_dwordx4 v[64:67], v[70:71], off
	global_load_dwordx4 v[2:5], v[2:3], off
.LBB0_932:
	s_or_b64 exec, exec, s[6:7]
	v_readlane_b32 s6, v250, 57
	v_readlane_b32 s7, v250, 58
	s_load_dwordx2 s[6:7], s[6:7], s13 offset:0x0
	v_readlane_b32 s30, v249, 60
	v_readlane_b32 s31, v249, 61
	s_lshl_b64 s[30:31], s[30:31], 2
	s_waitcnt lgkmcnt(0)
	s_add_u32 s34, s6, s30
	s_addc_u32 s35, s7, s31
	s_cmp_lg_u64 s[6:7], 0
	s_cselect_b64 s[36:37], -1, 0
	s_cmp_eq_u64 s[6:7], 0
	s_cbranch_scc1 .LBB0_934
	v_lshlrev_b32_e32 v0, 2, v11
	global_load_dword v72, v0, s[34:35] offset:128
	global_load_dword v0, v0, s[34:35]
	s_waitcnt vmcnt(0)
	v_pk_mul_f32 v[4:5], v[4:5], v[0:1] op_sel_hi:[1,0]
	v_pk_mul_f32 v[2:3], v[2:3], v[0:1] op_sel_hi:[1,0]
.LBB0_934:
	v_lshl_add_u32 v11, v10, 2, s25
	s_movk_i32 s6, 0x84
	v_mad_u32_u24 v0, v9, s6, v11
	s_waitcnt vmcnt(0)
	ds_write2_b32 v0, v2, v3 offset1:1
	ds_write2_b32 v0, v4, v5 offset0:2 offset1:3
	v_mov_b32_e32 v2, v1
	v_mov_b32_e32 v3, v1
	v_mov_b32_e32 v0, v1
	v_mov_b64_e32 v[4:5], v[2:3]
	v_or_b32_e32 v16, 8, v9
	v_mov_b64_e32 v[2:3], v[0:1]
	s_and_saveexec_b64 s[6:7], s[28:29]
	s_cbranch_execz .LBB0_936
	v_or_b32_e32 v0, s12, v16
	v_mul_u32_u24_e32 v0, 0x22a4, v0
	v_lshlrev_b32_e32 v0, 2, v0
	v_lshl_add_u64 v[2:3], v[6:7], 0, v[0:1]
	v_mov_b64_e32 v[2:3], v[40:41]
	v_mov_b64_e32 v[4:5], v[42:43]

.LBB0_938:
	v_mul_u32_u24_e32 v0, 0x84, v9
	v_add_u32_e32 v11, v0, v11
	v_add_u32_e32 v0, 0x420, v11
	s_waitcnt vmcnt(0)
	ds_write2_b32 v0, v2, v3 offset1:1
	v_add_u32_e32 v0, 0x428, v11
	v_mov_b32_e32 v2, v1
	v_mov_b32_e32 v3, v1
	ds_write2_b32 v0, v4, v5 offset1:1
	v_mov_b32_e32 v0, v1
	v_mov_b64_e32 v[4:5], v[2:3]
	v_or_b32_e32 v15, 16, v9
	v_mov_b64_e32 v[2:3], v[0:1]
	s_and_saveexec_b64 s[6:7], s[28:29]
	s_cbranch_execz .LBB0_940
	v_or_b32_e32 v0, s12, v15
	v_mul_u32_u24_e32 v0, 0x22a4, v0
	v_lshlrev_b32_e32 v0, 2, v0
	v_lshl_add_u64 v[2:3], v[6:7], 0, v[0:1]
	v_mov_b64_e32 v[2:3], v[44:45]
	v_mov_b64_e32 v[4:5], v[46:47]

.LBB0_942:
	v_add_u32_e32 v0, 0x840, v11
	s_waitcnt vmcnt(0)
	ds_write2_b32 v0, v2, v3 offset1:1
	v_add_u32_e32 v0, 0x848, v11
	v_mov_b32_e32 v2, v1
	v_mov_b32_e32 v3, v1
	ds_write2_b32 v0, v4, v5 offset1:1
	v_mov_b32_e32 v0, v1
	v_mov_b64_e32 v[4:5], v[2:3]
	v_or_b32_e32 v14, 24, v9
	v_mov_b64_e32 v[2:3], v[0:1]
	s_and_saveexec_b64 s[6:7], s[28:29]
	s_cbranch_execz .LBB0_944
	v_or_b32_e32 v0, s12, v14
	v_mul_u32_u24_e32 v0, 0x22a4, v0
	v_lshlrev_b32_e32 v0, 2, v0
	v_lshl_add_u64 v[2:3], v[6:7], 0, v[0:1]
	v_mov_b64_e32 v[2:3], v[48:49]
	v_mov_b64_e32 v[4:5], v[50:51]

.LBB0_946:
	v_add_u32_e32 v0, 0xc60, v11
	s_waitcnt vmcnt(0)
	ds_write2_b32 v0, v2, v3 offset1:1
	v_add_u32_e32 v0, 0xc68, v11
	v_mov_b32_e32 v2, v1
	v_mov_b32_e32 v3, v1
	ds_write2_b32 v0, v4, v5 offset1:1
	v_mov_b32_e32 v0, v1
	v_mov_b64_e32 v[4:5], v[2:3]
	v_mov_b64_e32 v[2:3], v[0:1]
	s_and_saveexec_b64 s[6:7], s[28:29]
	s_cbranch_execz .LBB0_948
	v_or3_b32 v0, v9, s12, 32
	v_mul_u32_u24_e32 v0, 0x22a4, v0
	v_lshlrev_b32_e32 v0, 2, v0
	v_lshl_add_u64 v[2:3], v[6:7], 0, v[0:1]
	v_mov_b64_e32 v[2:3], v[52:53]
	v_mov_b64_e32 v[4:5], v[54:55]

.LBB0_950:
	v_add_u32_e32 v0, 0x1080, v11
	s_waitcnt vmcnt(0)
	ds_write2_b32 v0, v2, v3 offset1:1
	v_add_u32_e32 v0, 0x1088, v11
	v_mov_b32_e32 v2, v1
	v_mov_b32_e32 v3, v1
	ds_write2_b32 v0, v4, v5 offset1:1
	v_mov_b32_e32 v0, v1
	v_mov_b64_e32 v[4:5], v[2:3]
	v_mov_b64_e32 v[2:3], v[0:1]
	s_and_saveexec_b64 s[6:7], s[28:29]
	s_cbranch_execz .LBB0_952
	v_or3_b32 v0, v9, s12, 40
	v_mul_u32_u24_e32 v0, 0x22a4, v0
	v_lshlrev_b32_e32 v0, 2, v0
	v_lshl_add_u64 v[2:3], v[6:7], 0, v[0:1]
	v_mov_b64_e32 v[2:3], v[56:57]
	v_mov_b64_e32 v[4:5], v[58:59]

.LBB0_954:
	v_add_u32_e32 v0, 0x14a0, v11
	s_waitcnt vmcnt(0)
	ds_write2_b32 v0, v2, v3 offset1:1
	v_add_u32_e32 v0, 0x14a8, v11
	v_mov_b32_e32 v2, v1
	v_mov_b32_e32 v3, v1
	ds_write2_b32 v0, v4, v5 offset1:1
	v_mov_b32_e32 v0, v1
	v_mov_b64_e32 v[4:5], v[2:3]
	v_mov_b64_e32 v[2:3], v[0:1]
	s_and_saveexec_b64 s[6:7], s[28:29]
	s_cbranch_execz .LBB0_956
	v_or3_b32 v0, v9, s12, 48
	v_mul_u32_u24_e32 v0, 0x22a4, v0
	v_lshlrev_b32_e32 v0, 2, v0
	v_lshl_add_u64 v[2:3], v[6:7], 0, v[0:1]
	v_mov_b64_e32 v[2:3], v[60:61]
	v_mov_b64_e32 v[4:5], v[62:63]

.LBB0_958:
	v_add_u32_e32 v0, 0x18c0, v11
	s_waitcnt vmcnt(0)
	ds_write2_b32 v0, v2, v3 offset1:1
	v_add_u32_e32 v0, 0x18c8, v11
	v_mov_b32_e32 v2, v1
	v_mov_b32_e32 v3, v1
	ds_write2_b32 v0, v4, v5 offset1:1
	v_mov_b32_e32 v0, v1
	v_mov_b64_e32 v[4:5], v[2:3]
	v_mov_b64_e32 v[2:3], v[0:1]
	s_and_saveexec_b64 s[6:7], s[28:29]
	s_cbranch_execz .LBB0_960
	v_or3_b32 v0, v9, s12, 56
	v_mul_u32_u24_e32 v0, 0x22a4, v0
	v_lshlrev_b32_e32 v0, 2, v0
	v_lshl_add_u64 v[2:3], v[6:7], 0, v[0:1]
	v_mov_b64_e32 v[2:3], v[64:65]
	v_mov_b64_e32 v[4:5], v[66:67]

.LBB0_1011:
	s_and_b64 vcc, exec, s[6:7]
	s_cbranch_vccz .LBB0_1276
	s_mov_b32 s6, 32
	v_readlane_b32 s10, v250, 57
	v_readlane_b32 s11, v250, 58
	s_load_dwordx2 s[6:7], s[10:11], s6 offset:0x0
	v_readlane_b32 s10, v248, 0
	v_and_b32_e32 v3, 7, v13
	v_lshlrev_b32_e32 v2, 4, v3
	v_lshrrev_b32_e32 v10, 3, v12
	s_waitcnt lgkmcnt(0)
	s_add_u32 s10, s6, s10
	v_readlane_b32 s6, v249, 8
	s_mul_hi_u32 s6, s6, 0xb00000
	s_addc_u32 s11, s7, s6
	s_lshl_b32 s6, s26, 1
	s_add_i32 s6, s6, 0x1ea00
	s_and_b32 s7, s6, 0x1ffc0
	s_lshl_b32 s6, s26, 5
	s_and_b32 s6, s6, 0x3e0
	v_lshl_or_b32 v0, s6, 2, v2
	v_lshl_add_u64 v[8:9], s[10:11], 0, v[0:1]
	v_or_b32_e32 v0, s7, v10
	v_lshlrev_b32_e32 v0, 12, v0
	v_lshl_add_u64 v[4:5], v[8:9], 0, v[0:1]
	v_mov_b32_e32 v68, 0x8000
	v_mov_b32_e32 v69, 0
	v_lshl_add_u64 v[70:71], v[4:5], 0, v[68:69]
	global_load_dwordx4 v[40:43], v[70:71], off
	v_lshl_add_u64 v[70:71], v[70:71], 0, v[68:69]
	global_load_dwordx4 v[44:47], v[70:71], off
	v_lshl_add_u64 v[70:71], v[70:71], 0, v[68:69]
	global_load_dwordx4 v[48:51], v[70:71], off
	v_lshl_add_u64 v[70:71], v[70:71], 0, v[68:69]
	global_load_dwordx4 v[52:55], v[70:71], off
	v_lshl_add_u64 v[70:71], v[70:71], 0, v[68:69]
	global_load_dwordx4 v[56:59], v[70:71], off
	v_lshl_add_u64 v[70:71], v[70:71], 0, v[68:69]
	global_load_dwordx4 v[60:63], v[70:71], off
	v_lshl_add_u64 v[70:71], v[70:71], 0, v[68:69]
	global_load_dwordx4 v[64:67], v[70:71], off
	global_load_dwordx4 v[4:7], v[4:5], off
	v_mul_u32_u24_e32 v11, 0x84, v10
	v_add3_u32 v11, s25, v2, v11
	v_or_b32_e32 v28, 8, v10
	v_add_u32_e32 v14, 0x420, v11
	v_or_b32_e32 v29, 16, v10
	v_or_b32_e32 v30, 24, v10
	v_readlane_b32 s10, v248, 1
	v_or_b32_e32 v26, s6, v10
	s_waitcnt vmcnt(0)
	ds_write2_b32 v11, v4, v5 offset1:1
	ds_write2_b32 v11, v6, v7 offset0:2 offset1:3
	v_or_b32_e32 v4, s7, v28
	v_lshlrev_b32_e32 v4, 12, v4
	v_mov_b32_e32 v5, v1
	v_lshl_add_u64 v[4:5], v[8:9], 0, v[4:5]
	v_mov_b64_e32 v[4:5], v[40:41]
	v_mov_b64_e32 v[6:7], v[42:43]
	s_waitcnt vmcnt(0)
	ds_write2_b32 v14, v4, v5 offset1:1
	v_add_u32_e32 v4, 0x428, v11
	ds_write2_b32 v4, v6, v7 offset1:1
	v_or_b32_e32 v4, s7, v29
	v_lshlrev_b32_e32 v4, 12, v4
	v_mov_b32_e32 v5, v1
	v_lshl_add_u64 v[4:5], v[8:9], 0, v[4:5]
	v_mov_b64_e32 v[4:5], v[44:45]
	v_mov_b64_e32 v[6:7], v[46:47]
	v_add_u32_e32 v14, 0x840, v11
	s_waitcnt vmcnt(0)
	ds_write2_b32 v14, v4, v5 offset1:1
	v_add_u32_e32 v4, 0x848, v11
	ds_write2_b32 v4, v6, v7 offset1:1
	v_or_b32_e32 v4, s7, v30
	v_lshlrev_b32_e32 v4, 12, v4
	v_mov_b32_e32 v5, v1
	v_lshl_add_u64 v[4:5], v[8:9], 0, v[4:5]
	v_mov_b64_e32 v[4:5], v[48:49]
	v_mov_b64_e32 v[6:7], v[50:51]
	v_add_u32_e32 v14, 0xc60, v11
	s_lshl_b32 s7, s7, 1
	s_add_u32 s10, s10, s7
	v_readlane_b32 s7, v248, 2
	s_addc_u32 s11, s7, 0
	s_waitcnt vmcnt(0)
	ds_write2_b32 v14, v4, v5 offset1:1
	v_add_u32_e32 v4, 0xc68, v11
	ds_write2_b32 v4, v6, v7 offset1:1
	v_or_b32_e32 v4, 0x20000, v0
	v_mov_b32_e32 v5, v1
	v_lshl_add_u64 v[4:5], v[8:9], 0, v[4:5]
	v_mov_b64_e32 v[4:5], v[52:53]
	v_mov_b64_e32 v[6:7], v[54:55]
	v_add_u32_e32 v14, 0x1080, v11
	s_waitcnt vmcnt(0)
	ds_write2_b32 v14, v4, v5 offset1:1
	v_add_u32_e32 v4, 0x1088, v11
	ds_write2_b32 v4, v6, v7 offset1:1
	v_or_b32_e32 v4, 0x28000, v0
	v_mov_b32_e32 v5, v1
	v_lshl_add_u64 v[4:5], v[8:9], 0, v[4:5]
	v_mov_b64_e32 v[4:5], v[56:57]
	v_mov_b64_e32 v[6:7], v[58:59]
	v_add_u32_e32 v14, 0x14a0, v11
	s_waitcnt vmcnt(0)
	ds_write2_b32 v14, v4, v5 offset1:1
	v_add_u32_e32 v4, 0x14a8, v11
	ds_write2_b32 v4, v6, v7 offset1:1
	v_or_b32_e32 v4, 0x30000, v0
	v_mov_b32_e32 v5, v1
	v_lshl_add_u64 v[4:5], v[8:9], 0, v[4:5]
	v_mov_b64_e32 v[4:5], v[60:61]
	v_mov_b64_e32 v[6:7], v[62:63]
	v_add_u32_e32 v14, 0x18c0, v11
	v_or_b32_e32 v0, 0x38000, v0
	s_waitcnt vmcnt(0)
	ds_write2_b32 v14, v4, v5 offset1:1
	v_add_u32_e32 v4, 0x18c8, v11
	ds_write2_b32 v4, v6, v7 offset1:1
	v_lshl_add_u64 v[4:5], v[8:9], 0, v[0:1]
	v_mov_b64_e32 v[4:5], v[64:65]
	v_mov_b64_e32 v[6:7], v[66:67]
	v_add_u32_e32 v0, 0x1ce0, v11
	s_waitcnt vmcnt(0)
	ds_write2_b32 v0, v4, v5 offset1:1
	v_add_u32_e32 v0, 0x1ce8, v11
	ds_write2_b32 v0, v6, v7 offset1:1
	v_mul_u32_u24_e32 v0, 0x420, v3
	v_lshlrev_b32_e32 v4, 2, v10
	s_waitcnt lgkmcnt(0)
	v_add3_u32 v31, s25, v0, v4
	ds_read2_b32 v[8:9], v31 offset0:198 offset1:206
	ds_read2_b32 v[10:11], v31 offset0:231 offset1:239
	ds_read2_b32 v[14:15], v31 offset0:132 offset1:140
	ds_read2_b32 v[16:17], v31 offset0:165 offset1:173
	ds_read2_b32 v[18:19], v31 offset0:66 offset1:74
	ds_read2_b32 v[20:21], v31 offset0:99 offset1:107
	ds_read2_b32 v[22:23], v31 offset0:33 offset1:41
	ds_read2_b32 v[24:25], v31 offset1:8
	v_mov_b32_e32 v3, v1
	v_mul_u32_u24_e32 v0, 0xb00, v26
	v_lshl_add_u64 v[2:3], s[10:11], 0, v[2:3]
	v_lshlrev_b32_e32 v0, 1, v0
	v_lshl_add_u64 v[26:27], v[2:3], 0, v[0:1]
	v_or_b32_e32 v0, s6, v28
	v_mul_u32_u24_e32 v0, 0xb00, v0
	s_waitcnt lgkmcnt(6)
	v_cvt_pk_bf16_f32 v7, v8, v10
	s_waitcnt lgkmcnt(4)
	v_cvt_pk_bf16_f32 v6, v14, v16
	s_waitcnt lgkmcnt(2)
	v_cvt_pk_bf16_f32 v5, v18, v20
	s_waitcnt lgkmcnt(0)
	v_cvt_pk_bf16_f32 v4, v24, v22
	v_lshlrev_b32_e32 v0, 1, v0
	global_store_dwordx4 v[26:27], v[4:7], off
	s_nop 1
	v_cvt_pk_bf16_f32 v7, v9, v11
	v_cvt_pk_bf16_f32 v6, v15, v17
	v_cvt_pk_bf16_f32 v5, v19, v21
	v_cvt_pk_bf16_f32 v4, v25, v23
	v_lshl_add_u64 v[8:9], v[2:3], 0, v[0:1]
	global_store_dwordx4 v[8:9], v[4:7], off
	v_or_b32_e32 v0, s6, v29
	ds_read2_b32 v[8:9], v31 offset0:214 offset1:222
	ds_read2_b32 v[10:11], v31 offset0:247 offset1:255
	ds_read2_b32 v[14:15], v31 offset0:148 offset1:156
	ds_read2_b32 v[16:17], v31 offset0:181 offset1:189
	ds_read2_b32 v[18:19], v31 offset0:82 offset1:90
	ds_read2_b32 v[20:21], v31 offset0:115 offset1:123
	ds_read2_b32 v[22:23], v31 offset0:16 offset1:24
	ds_read2_b32 v[24:25], v31 offset0:49 offset1:57
	v_mul_u32_u24_e32 v0, 0xb00, v0
	v_lshlrev_b32_e32 v0, 1, v0
	v_lshl_add_u64 v[26:27], v[2:3], 0, v[0:1]
	v_or_b32_e32 v0, s6, v30
	v_mul_u32_u24_e32 v0, 0xb00, v0
	s_waitcnt lgkmcnt(6)
	v_cvt_pk_bf16_f32 v7, v8, v10
	s_waitcnt lgkmcnt(4)
	v_cvt_pk_bf16_f32 v6, v14, v16
	s_waitcnt lgkmcnt(2)
	v_cvt_pk_bf16_f32 v5, v18, v20
	s_waitcnt lgkmcnt(0)
	v_cvt_pk_bf16_f32 v4, v22, v24
	v_lshlrev_b32_e32 v0, 1, v0
	global_store_dwordx4 v[26:27], v[4:7], off
	v_lshl_add_u64 v[2:3], v[2:3], 0, v[0:1]
	s_mov_b64 s[6:7], 0
	v_cvt_pk_bf16_f32 v7, v9, v11
	v_cvt_pk_bf16_f32 v6, v15, v17
	v_cvt_pk_bf16_f32 v5, v19, v21
	v_cvt_pk_bf16_f32 v4, v23, v25
	global_store_dwordx4 v[2:3], v[4:7], off
	s_waitcnt lgkmcnt(0)

.LBB0_1014:
	s_mov_b32 s6, 24
	v_readlane_b32 s12, v250, 57
	v_readlane_b32 s13, v250, 58
	s_load_dwordx2 s[6:7], s[12:13], s6 offset:0x0
	s_mov_b32 s10, 8
	s_load_dwordx2 s[10:11], s[12:13], s10 offset:0x0
	v_readlane_b32 s12, v248, 0
	s_waitcnt lgkmcnt(0)
	s_add_u32 s12, s6, s12
	s_addc_u32 s13, s7, 0
	v_readlane_b32 s6, v249, 60
	v_readlane_b32 s7, v249, 61
	s_lshl_b64 s[6:7], s[6:7], 2
	s_add_u32 s30, s10, s6
	s_addc_u32 s31, s11, s7
	s_add_i32 s6, s26, 0xfa80
	s_and_b32 s7, s6, 0xffff
	s_mul_i32 s7, s7, 0xba2f
	s_lshr_b32 s14, s7, 16
	s_lshr_b32 s7, s7, 22
	s_mulk_i32 s7, 0x58
	s_sub_i32 s6, s6, s7
	s_lshl_b32 s6, s6, 5
	v_and_b32_e32 v10, 7, v13
	s_and_b32 s6, s6, 0xffe0
	v_lshlrev_b32_e32 v9, 2, v10
	s_and_b32 s7, s14, 0xffc0
	v_or_b32_e32 v0, s6, v9
	v_lshrrev_b32_e32 v8, 3, v12
	v_lshlrev_b32_e32 v0, 2, v0
	v_or_b32_e32 v11, s7, v8
	v_lshl_add_u64 v[6:7], s[12:13], 0, v[0:1]
	v_mul_u32_u24_e32 v0, 0xb00, v11
	v_lshlrev_b32_e32 v0, 2, v0
	v_lshl_add_u64 v[2:3], v[6:7], 0, v[0:1]
	v_mov_b32_e32 v68, 0x16000
	v_mov_b32_e32 v69, 0
	v_lshl_add_u64 v[70:71], v[2:3], 0, v[68:69]
	global_load_dwordx4 v[40:43], v[70:71], off
	v_lshl_add_u64 v[70:71], v[70:71], 0, v[68:69]
	global_load_dwordx4 v[44:47], v[70:71], off
	v_lshl_add_u64 v[70:71], v[70:71], 0, v[68:69]
	global_load_dwordx4 v[48:51], v[70:71], off
	v_lshl_add_u64 v[70:71], v[70:71], 0, v[68:69]
	global_load_dwordx4 v[52:55], v[70:71], off
	v_lshl_add_u64 v[70:71], v[70:71], 0, v[68:69]
	global_load_dwordx4 v[56:59], v[70:71], off
	v_lshl_add_u64 v[70:71], v[70:71], 0, v[68:69]
	global_load_dwordx4 v[60:63], v[70:71], off
	v_lshl_add_u64 v[70:71], v[70:71], 0, v[68:69]
	global_load_dwordx4 v[64:67], v[70:71], off
	global_load_dwordx4 v[2:5], v[2:3], off
	s_cmp_lg_u64 s[10:11], 0
	s_cselect_b64 s[34:35], -1, 0
	s_cmp_eq_u64 s[10:11], 0
	s_cbranch_scc1 .LBB0_1016
	v_lshlrev_b32_e32 v0, 2, v11
	global_load_dword v72, v0, s[30:31] offset:128
	global_load_dword v0, v0, s[30:31]
	s_waitcnt vmcnt(0)
	v_pk_mul_f32 v[4:5], v[4:5], v[0:1] op_sel_hi:[1,0]
	v_pk_mul_f32 v[2:3], v[2:3], v[0:1] op_sel_hi:[1,0]
.LBB0_1016:
	v_lshl_add_u32 v11, v9, 2, s25
	s_movk_i32 s10, 0x84
	v_mad_u32_u24 v0, v8, s10, v11
	v_or_b32_e32 v9, 8, v8
	s_waitcnt vmcnt(0)
	ds_write2_b32 v0, v2, v3 offset1:1
	ds_write2_b32 v0, v4, v5 offset0:2 offset1:3
	v_or_b32_e32 v0, s7, v9
	v_mul_u32_u24_e32 v0, 0xb00, v0
	v_lshlrev_b32_e32 v0, 2, v0
	v_lshl_add_u64 v[2:3], v[6:7], 0, v[0:1]
	v_mov_b64_e32 v[2:3], v[40:41]
	v_mov_b64_e32 v[4:5], v[42:43]
	v_cndmask_b32_e64 v0, 0, 1, s[34:35]
	v_cmp_ne_u32_e64 s[28:29], 1, v0
	s_andn2_b64 vcc, exec, s[34:35]
	v_add_lshl_u32 v15, v8, s7, 2
	s_cbranch_vccnz .LBB0_1018
	global_load_dword v0, v15, s[30:31] offset:32
	s_waitcnt vmcnt(0)
	v_pk_mul_f32 v[4:5], v[4:5], v[0:1] op_sel_hi:[1,0]
	v_pk_mul_f32 v[2:3], v[2:3], v[0:1] op_sel_hi:[1,0]
.LBB0_1018:
	v_mul_u32_u24_e32 v0, 0x84, v8
	v_add_u32_e32 v16, v0, v11
	v_add_u32_e32 v0, 0x420, v16
	s_waitcnt vmcnt(0)
	ds_write2_b32 v0, v2, v3 offset1:1
	v_add_u32_e32 v0, 0x428, v16
	v_or_b32_e32 v11, 16, v8
	ds_write2_b32 v0, v4, v5 offset1:1
	v_or_b32_e32 v0, s7, v11
	v_mul_u32_u24_e32 v0, 0xb00, v0
	v_lshlrev_b32_e32 v0, 2, v0
	v_lshl_add_u64 v[2:3], v[6:7], 0, v[0:1]
	v_mov_b64_e32 v[2:3], v[44:45]
	v_mov_b64_e32 v[4:5], v[46:47]
	s_and_b64 vcc, exec, s[28:29]
	s_cbranch_vccnz .LBB0_1020
	global_load_dword v0, v15, s[30:31] offset:64
	s_waitcnt vmcnt(0)
	v_pk_mul_f32 v[4:5], v[4:5], v[0:1] op_sel_hi:[1,0]
	v_pk_mul_f32 v[2:3], v[2:3], v[0:1] op_sel_hi:[1,0]
.LBB0_1020:
	v_add_u32_e32 v0, 0x840, v16
	s_waitcnt vmcnt(0)
	ds_write2_b32 v0, v2, v3 offset1:1
	v_add_u32_e32 v0, 0x848, v16
	v_or_b32_e32 v14, 24, v8
	ds_write2_b32 v0, v4, v5 offset1:1
	v_or_b32_e32 v0, s7, v14
	v_mul_u32_u24_e32 v0, 0xb00, v0
	v_lshlrev_b32_e32 v0, 2, v0
	v_lshl_add_u64 v[2:3], v[6:7], 0, v[0:1]
	v_mov_b64_e32 v[2:3], v[48:49]
	v_mov_b64_e32 v[4:5], v[50:51]
	s_and_b64 vcc, exec, s[28:29]
	s_cbranch_vccnz .LBB0_1022
	global_load_dword v0, v15, s[30:31] offset:96
	s_waitcnt vmcnt(0)
	v_pk_mul_f32 v[4:5], v[4:5], v[0:1] op_sel_hi:[1,0]
	v_pk_mul_f32 v[2:3], v[2:3], v[0:1] op_sel_hi:[1,0]
.LBB0_1022:
	v_add_u32_e32 v0, 0xc60, v16
	s_waitcnt vmcnt(0)
	ds_write2_b32 v0, v2, v3 offset1:1
	v_add_u32_e32 v0, 0xc68, v16
	ds_write2_b32 v0, v4, v5 offset1:1
	v_or3_b32 v0, v8, s7, 32
	v_mul_u32_u24_e32 v0, 0xb00, v0
	v_lshlrev_b32_e32 v0, 2, v0
	v_lshl_add_u64 v[2:3], v[6:7], 0, v[0:1]
	v_mov_b64_e32 v[2:3], v[52:53]
	v_mov_b64_e32 v[4:5], v[54:55]
	s_and_b64 vcc, exec, s[28:29]
	s_cbranch_vccnz .LBB0_1024
	global_load_dword v0, v15, s[30:31] offset:128
	s_waitcnt vmcnt(0)
	v_pk_mul_f32 v[4:5], v[4:5], v[0:1] op_sel_hi:[1,0]
	v_pk_mul_f32 v[2:3], v[2:3], v[0:1] op_sel_hi:[1,0]
.LBB0_1024:
	v_add_u32_e32 v0, 0x1080, v16
	s_waitcnt vmcnt(0)
	ds_write2_b32 v0, v2, v3 offset1:1
	v_add_u32_e32 v0, 0x1088, v16
	ds_write2_b32 v0, v4, v5 offset1:1
	v_or3_b32 v0, v8, s7, 40
	v_mul_u32_u24_e32 v0, 0xb00, v0
	v_lshlrev_b32_e32 v0, 2, v0
	v_lshl_add_u64 v[2:3], v[6:7], 0, v[0:1]
	v_mov_b64_e32 v[2:3], v[56:57]
	v_mov_b64_e32 v[4:5], v[58:59]
	s_and_b64 vcc, exec, s[28:29]
	s_cbranch_vccnz .LBB0_1026
	global_load_dword v0, v15, s[30:31] offset:160
	s_waitcnt vmcnt(0)
	v_pk_mul_f32 v[4:5], v[4:5], v[0:1] op_sel_hi:[1,0]
	v_pk_mul_f32 v[2:3], v[2:3], v[0:1] op_sel_hi:[1,0]
.LBB0_1026:
	v_add_u32_e32 v0, 0x14a0, v16
	s_waitcnt vmcnt(0)
	ds_write2_b32 v0, v2, v3 offset1:1
	v_add_u32_e32 v0, 0x14a8, v16
	ds_write2_b32 v0, v4, v5 offset1:1
	v_or3_b32 v0, v8, s7, 48
	v_mul_u32_u24_e32 v0, 0xb00, v0
	v_lshlrev_b32_e32 v0, 2, v0
	v_lshl_add_u64 v[2:3], v[6:7], 0, v[0:1]
	v_mov_b64_e32 v[2:3], v[60:61]
	v_mov_b64_e32 v[4:5], v[62:63]
	s_and_b64 vcc, exec, s[28:29]
	s_cbranch_vccnz .LBB0_1028
	global_load_dword v0, v15, s[30:31] offset:192
	s_waitcnt vmcnt(0)
	v_pk_mul_f32 v[4:5], v[4:5], v[0:1] op_sel_hi:[1,0]
	v_pk_mul_f32 v[2:3], v[2:3], v[0:1] op_sel_hi:[1,0]
.LBB0_1028:
	v_add_u32_e32 v0, 0x18c0, v16
	s_waitcnt vmcnt(0)
	ds_write2_b32 v0, v2, v3 offset1:1
	v_add_u32_e32 v0, 0x18c8, v16
	ds_write2_b32 v0, v4, v5 offset1:1
	v_or3_b32 v0, v8, s7, 56
	v_mul_u32_u24_e32 v0, 0xb00, v0
	v_lshlrev_b32_e32 v0, 2, v0
	v_lshl_add_u64 v[2:3], v[6:7], 0, v[0:1]
	v_mov_b64_e32 v[2:3], v[64:65]
	v_mov_b64_e32 v[4:5], v[66:67]
	s_and_b64 vcc, exec, s[28:29]
	s_cbranch_vccnz .LBB0_1030
	global_load_dword v0, v15, s[30:31] offset:224
	s_waitcnt vmcnt(0)
	v_pk_mul_f32 v[4:5], v[4:5], v[0:1] op_sel_hi:[1,0]
	v_pk_mul_f32 v[2:3], v[2:3], v[0:1] op_sel_hi:[1,0]

.LBB0_1032:
	s_andn2_b64 vcc, exec, s[6:7]
	s_cbranch_vccnz .LBB0_1051
	s_mov_b32 s6, 16
	v_readlane_b32 s12, v250, 57
	v_readlane_b32 s13, v250, 58
	s_load_dwordx2 s[6:7], s[12:13], s6 offset:0x0
	s_mov_b32 s10, 8
	s_load_dwordx2 s[12:13], s[12:13], s10 offset:0x0
	v_readlane_b32 s10, v248, 0
	s_waitcnt lgkmcnt(0)
	s_add_u32 s6, s6, s10
	v_readlane_b32 s10, v249, 60
	v_readlane_b32 s11, v249, 61
	s_addc_u32 s7, s7, 0
	s_lshl_b64 s[10:11], s[10:11], 2
	s_add_u32 s34, s12, s10
	s_mul_hi_i32 s10, s26, 0x2e8ba2e9
	s_addc_u32 s35, s13, s11
	s_lshr_b32 s11, s10, 31
	s_ashr_i32 s10, s10, 4
	s_add_i32 s10, s10, s11
	s_mul_i32 s11, s10, 0x58
	s_sub_i32 s11, s26, s11
	v_and_b32_e32 v0, 7, v13
	s_lshl_b32 s30, s10, 6
	s_lshl_b32 s10, s11, 5
	v_lshlrev_b32_e32 v11, 2, v0
	v_or_b32_e32 v2, s10, v11
	v_ashrrev_i32_e32 v3, 31, v2
	v_lshrrev_b32_e32 v10, 3, v12
	v_lshl_add_u64 v[6:7], v[2:3], 2, s[6:7]
	v_or_b32_e32 v8, s30, v10
	s_movk_i32 s11, 0x2c00
	v_mad_i64_i32 v[2:3], s[6:7], v8, s11, v[6:7]
	v_mov_b32_e32 v68, 0x16000
	v_mov_b32_e32 v69, 0
	v_lshl_add_u64 v[70:71], v[2:3], 0, v[68:69]
	global_load_dwordx4 v[40:43], v[70:71], off
	v_lshl_add_u64 v[70:71], v[70:71], 0, v[68:69]
	global_load_dwordx4 v[44:47], v[70:71], off
	v_lshl_add_u64 v[70:71], v[70:71], 0, v[68:69]
	global_load_dwordx4 v[48:51], v[70:71], off
	v_lshl_add_u64 v[70:71], v[70:71], 0, v[68:69]
	global_load_dwordx4 v[52:55], v[70:71], off
	v_lshl_add_u64 v[70:71], v[70:71], 0, v[68:69]
	global_load_dwordx4 v[56:59], v[70:71], off
	v_lshl_add_u64 v[70:71], v[70:71], 0, v[68:69]
	global_load_dwordx4 v[60:63], v[70:71], off
	v_lshl_add_u64 v[70:71], v[70:71], 0, v[68:69]
	global_load_dwordx4 v[64:67], v[70:71], off
	global_load_dwordx4 v[2:5], v[2:3], off
	s_cmp_lg_u64 s[12:13], 0
	s_cselect_b64 s[36:37], -1, 0
	s_cmp_eq_u64 s[12:13], 0
	s_cbranch_scc1 .LBB0_1035
	v_ashrrev_i32_e32 v9, 31, v8
	v_lshl_add_u64 v[8:9], v[8:9], 2, s[34:35]
	global_load_dword v72, v[8:9], off offset:128
	global_load_dword v8, v[8:9], off
	s_waitcnt vmcnt(0)
	v_pk_mul_f32 v[4:5], v[4:5], v[8:9] op_sel_hi:[1,0]
	v_pk_mul_f32 v[2:3], v[2:3], v[8:9] op_sel_hi:[1,0]
.LBB0_1035:
	v_lshl_add_u32 v8, v11, 2, s25
	s_movk_i32 s6, 0x84
	v_mad_u32_u24 v9, v10, s6, v8
	v_or_b32_e32 v13, 8, v10
	s_waitcnt vmcnt(0)
	ds_write2_b32 v9, v2, v3 offset1:1
	ds_write2_b32 v9, v4, v5 offset0:2 offset1:3
	v_or_b32_e32 v2, s30, v13
	v_mad_i64_i32 v[2:3], s[6:7], v2, s11, v[6:7]
	v_mov_b64_e32 v[2:3], v[40:41]
	v_mov_b64_e32 v[4:5], v[42:43]
	v_cndmask_b32_e64 v9, 0, 1, s[36:37]
	v_cmp_ne_u32_e64 s[28:29], 1, v9
	s_andn2_b64 vcc, exec, s[36:37]
	s_cbranch_vccnz .LBB0_1037
	s_ashr_i32 s31, s30, 31
	v_mov_b32_e32 v11, v1
	v_lshl_add_u64 v[14:15], s[30:31], 0, v[10:11]
	v_lshl_add_u64 v[14:15], v[14:15], 2, s[34:35]
	global_load_dword v14, v[14:15], off offset:32
	s_waitcnt vmcnt(0)
	v_pk_mul_f32 v[4:5], v[4:5], v[14:15] op_sel_hi:[1,0]
	v_pk_mul_f32 v[2:3], v[2:3], v[14:15] op_sel_hi:[1,0]
.LBB0_1037:
	v_mul_u32_u24_e32 v9, 0x84, v10
	v_add_u32_e32 v16, v9, v8
	v_add_u32_e32 v8, 0x420, v16
	s_waitcnt vmcnt(0)
	ds_write2_b32 v8, v2, v3 offset1:1
	v_add_u32_e32 v2, 0x428, v16
	v_or_b32_e32 v14, 16, v10
	ds_write2_b32 v2, v4, v5 offset1:1
	v_or_b32_e32 v2, s30, v14
	v_mad_i64_i32 v[2:3], s[6:7], v2, s11, v[6:7]
	v_mov_b64_e32 v[2:3], v[44:45]
	v_mov_b64_e32 v[4:5], v[46:47]
	s_and_b64 vcc, exec, s[28:29]
	s_cbranch_vccnz .LBB0_1039
	s_ashr_i32 s31, s30, 31
	v_mov_b32_e32 v11, v1
	v_lshl_add_u64 v[8:9], s[30:31], 0, v[10:11]
	v_lshl_add_u64 v[8:9], v[8:9], 2, s[34:35]
	global_load_dword v8, v[8:9], off offset:64
	s_waitcnt vmcnt(0)
	v_pk_mul_f32 v[4:5], v[4:5], v[8:9] op_sel_hi:[1,0]
	v_pk_mul_f32 v[2:3], v[2:3], v[8:9] op_sel_hi:[1,0]
.LBB0_1039:
	v_add_u32_e32 v8, 0x840, v16
	s_waitcnt vmcnt(0)
	ds_write2_b32 v8, v2, v3 offset1:1
	v_add_u32_e32 v2, 0x848, v16
	v_or_b32_e32 v15, 24, v10
	ds_write2_b32 v2, v4, v5 offset1:1
	v_or_b32_e32 v2, s30, v15
	v_mad_i64_i32 v[2:3], s[6:7], v2, s11, v[6:7]
	v_mov_b64_e32 v[2:3], v[48:49]
	v_mov_b64_e32 v[4:5], v[50:51]
	s_and_b64 vcc, exec, s[28:29]
	s_cbranch_vccnz .LBB0_1041
	s_ashr_i32 s31, s30, 31
	v_mov_b32_e32 v11, v1
	v_lshl_add_u64 v[8:9], s[30:31], 0, v[10:11]
	v_lshl_add_u64 v[8:9], v[8:9], 2, s[34:35]
	global_load_dword v8, v[8:9], off offset:96
	s_waitcnt vmcnt(0)
	v_pk_mul_f32 v[4:5], v[4:5], v[8:9] op_sel_hi:[1,0]
	v_pk_mul_f32 v[2:3], v[2:3], v[8:9] op_sel_hi:[1,0]
.LBB0_1041:
	v_add_u32_e32 v8, 0xc60, v16
	s_waitcnt vmcnt(0)
	ds_write2_b32 v8, v2, v3 offset1:1
	v_add_u32_e32 v2, 0xc68, v16
	ds_write2_b32 v2, v4, v5 offset1:1
	v_or3_b32 v2, v10, s30, 32
	v_mad_i64_i32 v[2:3], s[6:7], v2, s11, v[6:7]
	v_mov_b64_e32 v[2:3], v[52:53]
	v_mov_b64_e32 v[4:5], v[54:55]
	s_and_b64 vcc, exec, s[28:29]
	s_cbranch_vccnz .LBB0_1043
	s_ashr_i32 s31, s30, 31
	v_mov_b32_e32 v11, v1
	v_lshl_add_u64 v[8:9], s[30:31], 0, v[10:11]
	v_lshl_add_u64 v[8:9], v[8:9], 2, s[34:35]
	global_load_dword v8, v[8:9], off offset:128
	s_waitcnt vmcnt(0)
	v_pk_mul_f32 v[4:5], v[4:5], v[8:9] op_sel_hi:[1,0]
	v_pk_mul_f32 v[2:3], v[2:3], v[8:9] op_sel_hi:[1,0]
.LBB0_1043:
	v_add_u32_e32 v8, 0x1080, v16
	s_waitcnt vmcnt(0)
	ds_write2_b32 v8, v2, v3 offset1:1
	v_add_u32_e32 v2, 0x1088, v16
	ds_write2_b32 v2, v4, v5 offset1:1
	v_or3_b32 v2, v10, s30, 40
	v_mad_i64_i32 v[2:3], s[6:7], v2, s11, v[6:7]
	v_mov_b64_e32 v[2:3], v[56:57]
	v_mov_b64_e32 v[4:5], v[58:59]
	s_and_b64 vcc, exec, s[28:29]
	s_cbranch_vccnz .LBB0_1045
	s_ashr_i32 s31, s30, 31
	v_mov_b32_e32 v11, v1
	v_lshl_add_u64 v[8:9], s[30:31], 0, v[10:11]
	v_lshl_add_u64 v[8:9], v[8:9], 2, s[34:35]
	global_load_dword v8, v[8:9], off offset:160
	s_waitcnt vmcnt(0)
	v_pk_mul_f32 v[4:5], v[4:5], v[8:9] op_sel_hi:[1,0]
	v_pk_mul_f32 v[2:3], v[2:3], v[8:9] op_sel_hi:[1,0]
.LBB0_1045:
	v_add_u32_e32 v8, 0x14a0, v16
	s_waitcnt vmcnt(0)
	ds_write2_b32 v8, v2, v3 offset1:1
	v_add_u32_e32 v2, 0x14a8, v16
	ds_write2_b32 v2, v4, v5 offset1:1
	v_or3_b32 v2, v10, s30, 48
	v_mad_i64_i32 v[2:3], s[6:7], v2, s11, v[6:7]
	v_mov_b64_e32 v[2:3], v[60:61]
	v_mov_b64_e32 v[4:5], v[62:63]
	s_and_b64 vcc, exec, s[28:29]
	s_cbranch_vccnz .LBB0_1047
	s_ashr_i32 s31, s30, 31
	v_mov_b32_e32 v11, v1
	v_lshl_add_u64 v[8:9], s[30:31], 0, v[10:11]
	v_lshl_add_u64 v[8:9], v[8:9], 2, s[34:35]
	global_load_dword v8, v[8:9], off offset:192
	s_waitcnt vmcnt(0)
	v_pk_mul_f32 v[4:5], v[4:5], v[8:9] op_sel_hi:[1,0]
	v_pk_mul_f32 v[2:3], v[2:3], v[8:9] op_sel_hi:[1,0]
.LBB0_1047:
	v_add_u32_e32 v8, 0x18c0, v16
	s_waitcnt vmcnt(0)
	ds_write2_b32 v8, v2, v3 offset1:1
	v_add_u32_e32 v2, 0x18c8, v16
	ds_write2_b32 v2, v4, v5 offset1:1
	v_or3_b32 v2, v10, s30, 56
	v_mad_i64_i32 v[2:3], s[6:7], v2, s11, v[6:7]
	v_mov_b64_e32 v[2:3], v[64:65]
	v_mov_b64_e32 v[4:5], v[66:67]
	s_and_b64 vcc, exec, s[36:37]
	s_cbranch_vccz .LBB0_1275
	s_ashr_i32 s31, s30, 31
	v_mov_b32_e32 v11, v1
	v_lshl_add_u64 v[6:7], s[30:31], 0, v[10:11]
	v_lshl_add_u64 v[6:7], v[6:7], 2, s[34:35]
	global_load_dword v6, v[6:7], off offset:224
	s_waitcnt vmcnt(0)
	v_pk_mul_f32 v[8:9], v[4:5], v[6:7] op_sel_hi:[1,0]
	v_pk_mul_f32 v[6:7], v[2:3], v[6:7] op_sel_hi:[1,0]
	s_cbranch_execnz .LBB0_1050
